# glu epilogue loads batched; merge GEMM loops re-pipelined (next-slice loads before MFMA block); adaLN GEMV prefetch ring
# speedup vs baseline: 1.0505x; 1.0505x over previous
.LBB0_105:
	v_mov_b32_e32 v3, v133
	s_lshl_b32 s6, s12, 20
	v_lshlrev_b32_e32 v0, 3, v3
	v_lshrrev_b32_e32 v4, 3, v3
	v_and_b32_e32 v156, 56, v0
	v_mul_lo_u32 v4, v4, s21
	v_add_lshl_u32 v168, v4, v156, 1
	v_add_u32_e32 v4, 0x100, v3
	v_lshrrev_b32_e32 v4, 3, v4
	v_mul_lo_u32 v4, v4, s21
	v_add_lshl_u32 v169, v4, v156, 1
	v_add_u32_e32 v4, 0x200, v3
	v_lshrrev_b32_e32 v4, 3, v4
	v_mul_lo_u32 v4, v4, s21
	v_add_lshl_u32 v170, v4, v156, 1
	v_add_u32_e32 v4, 0x300, v3
	v_lshrrev_b32_e32 v4, 3, v4
	v_mul_lo_u32 v4, v4, s21
	s_add_i32 s4, s11, s6
	v_and_b32_e32 v2, 31, v3
	v_lshlrev_b32_e32 v0, 7, v3
	v_add_lshl_u32 v171, v4, v156, 1
	v_lshrrev_b32_e32 v4, 1, v3
	s_mov_b32 s14, 0xfffffc0
	s_lshl_b32 s4, s4, 1
	v_and_b32_e32 v164, 0xfffffc00, v0
	v_and_or_b32 v5, v4, s14, v2
	v_and_b32_e32 v2, 16, v4
	s_add_u32 s4, s18, s4
	v_add_u32_e32 v165, 0x8000, v164
	v_add_u32_e32 v166, 0x10000, v164
	v_add_u32_e32 v167, 0x18000, v164
	v_mad_u64_u32 v[158:159], s[14:15], v5, s37, v[2:3]
	v_and_b32_e32 v3, 0x5f, v3
	s_mov_b32 s7, 1
	s_addc_u32 s5, s19, 0
	v_or_b32_e32 v0, v165, v156
	v_or_b32_e32 v160, v166, v156
	v_or_b32_e32 v162, v167, v156
	v_mad_u32_u24 v159, v3, s37, v2
	v_mov_b32_e32 v161, v156
	v_mov_b32_e32 v2, 0
	v_mov_b32_e32 v3, v152
	v_mov_b32_e32 v4, v152
	v_mov_b32_e32 v5, v152
	v_mov_b32_e32 v6, v152
	v_mov_b32_e32 v7, v152
	v_mov_b32_e32 v8, v152
	v_mov_b32_e32 v9, v152
	v_mov_b32_e32 v10, v152
	v_mov_b32_e32 v11, v152
	v_mov_b32_e32 v12, v152
	v_mov_b32_e32 v13, v152
	v_mov_b32_e32 v14, v152
	v_mov_b32_e32 v15, v152
	v_mov_b32_e32 v16, v152
	v_mov_b32_e32 v17, v152
	v_mov_b32_e32 v18, 0
	v_mov_b32_e32 v19, v152
	v_mov_b32_e32 v20, v152
	v_mov_b32_e32 v21, v152
	v_mov_b32_e32 v22, v152
	v_mov_b32_e32 v23, v152
	v_mov_b32_e32 v24, v152
	v_mov_b32_e32 v25, v152
	v_mov_b32_e32 v26, v152
	v_mov_b32_e32 v27, v152
	v_mov_b32_e32 v28, v152
	v_mov_b32_e32 v29, v152
	v_mov_b32_e32 v30, v152
	v_mov_b32_e32 v31, v152
	v_mov_b32_e32 v32, v152
	v_mov_b32_e32 v33, v152
	v_mov_b32_e32 v34, 0
	v_mov_b32_e32 v35, v152
	v_mov_b32_e32 v36, v152
	v_mov_b32_e32 v37, v152
	v_mov_b32_e32 v38, v152
	v_mov_b32_e32 v39, v152
	v_mov_b32_e32 v40, v152
	v_mov_b32_e32 v41, v152
	v_mov_b32_e32 v42, v152
	v_mov_b32_e32 v43, v152
	v_mov_b32_e32 v44, v152
	v_mov_b32_e32 v45, v152
	v_mov_b32_e32 v46, v152
	v_mov_b32_e32 v47, v152
	v_mov_b32_e32 v48, v152
	v_mov_b32_e32 v49, v152
	s_waitcnt vmcnt(3)
	v_mov_b32_e32 v50, 0
	s_waitcnt vmcnt(2)
	v_mov_b32_e32 v51, v152
	v_mov_b32_e32 v52, v152
	s_waitcnt vmcnt(1)
	v_mov_b32_e32 v53, v152
	v_mov_b32_e32 v54, v152
	v_mov_b32_e32 v55, v152
	v_mov_b32_e32 v56, v152
	v_mov_b32_e32 v57, v152
	v_mov_b32_e32 v58, v152
	v_mov_b32_e32 v59, v152
	v_mov_b32_e32 v60, v152
	v_mov_b32_e32 v61, v152
	v_mov_b32_e32 v62, v152
	v_mov_b32_e32 v63, v152
	v_mov_b32_e32 v64, v152
	v_mov_b32_e32 v65, v152
	v_lshlrev_b64 v[172:173], 1, v[0:1]
	v_or_b32_e32 v0, v161, v164
	v_mov_b32_e32 v163, v1
	v_mov_b32_e32 v161, v1
	v_lshlrev_b64 v[176:177], 1, v[0:1]
	v_lshlrev_b64 v[162:163], 1, v[162:163]
	v_lshlrev_b64 v[160:161], 1, v[160:161]
	v_lshl_add_u64 v[174:175], s[38:39], 0, v[172:173]
	v_lshl_add_u64 v[172:173], s[4:5], 0, v[172:173]
	v_lshl_add_u64 v[178:179], s[38:39], 0, v[176:177]
	v_lshl_add_u64 v[226:227], s[4:5], 0, v[162:163]
	v_lshl_add_u64 v[218:219], s[4:5], 0, v[160:161]
	v_lshl_add_u64 v[180:181], s[4:5], 0, v[176:177]
	v_lshl_add_u64 v[214:215], s[38:39], 0, v[160:161]
	v_lshl_add_u64 v[222:223], s[38:39], 0, v[162:163]
	global_load_dwordx4 v[160:163], v[172:173], off
	s_nop 0
	global_load_dwordx4 v[172:175], v[174:175], off
	s_nop 0
	global_load_dwordx4 v[176:179], v[178:179], off
	s_nop 0
	global_load_dwordx4 v[180:183], v[180:181], off
	s_nop 0
	global_load_dwordx4 v[214:217], v[214:215], off
	s_nop 0
	global_load_dwordx4 v[218:221], v[218:219], off
	s_nop 0
	global_load_dwordx4 v[222:225], v[222:223], off
	s_nop 0
	global_load_dwordx4 v[226:229], v[226:227], off
.LBB0_106:
	s_barrier
	s_waitcnt vmcnt(5)
	ds_write_b128 v168, v[176:179]
	s_waitcnt vmcnt(4)
	ds_write_b128 v168, v[180:183] offset:18432
	ds_write_b128 v169, v[172:175]
	ds_write_b128 v169, v[160:163] offset:18432
	s_waitcnt vmcnt(3)
	ds_write_b128 v170, v[214:217]
	s_waitcnt vmcnt(2)
	ds_write_b128 v170, v[218:221] offset:18432
	s_waitcnt vmcnt(1)
	ds_write_b128 v171, v[222:225]
	s_waitcnt vmcnt(0)
	ds_write_b128 v171, v[226:229] offset:18432
	s_waitcnt lgkmcnt(0)
	s_barrier
	s_min_u32 s14, s7, 15
	s_add_i32 s7, s7, 1
	s_cmp_lg_u32 s7, 17
	s_cbranch_scc0 .Lmg_noload_g1024
	v_lshl_or_b32 v161, s14, 6, v156
	v_or_b32_e32 v0, v161, v165
	v_or_b32_e32 v160, v161, v166
	v_or_b32_e32 v162, v161, v167
	v_lshlrev_b64 v[172:173], 1, v[0:1]
	v_or_b32_e32 v0, v161, v164
	v_mov_b32_e32 v163, v1
	v_mov_b32_e32 v161, v1
	v_lshlrev_b64 v[176:177], 1, v[0:1]
	v_lshlrev_b64 v[162:163], 1, v[162:163]
	v_lshlrev_b64 v[160:161], 1, v[160:161]
	v_lshl_add_u64 v[174:175], s[38:39], 0, v[172:173]
	v_lshl_add_u64 v[172:173], s[4:5], 0, v[172:173]
	v_lshl_add_u64 v[178:179], s[38:39], 0, v[176:177]
	v_lshl_add_u64 v[226:227], s[4:5], 0, v[162:163]
	v_lshl_add_u64 v[218:219], s[4:5], 0, v[160:161]
	v_lshl_add_u64 v[180:181], s[4:5], 0, v[176:177]
	v_lshl_add_u64 v[214:215], s[38:39], 0, v[160:161]
	v_lshl_add_u64 v[222:223], s[38:39], 0, v[162:163]
	global_load_dwordx4 v[160:163], v[172:173], off
	s_nop 0
	global_load_dwordx4 v[172:175], v[174:175], off
	s_nop 0
	global_load_dwordx4 v[176:179], v[178:179], off
	s_nop 0
	global_load_dwordx4 v[180:183], v[180:181], off
	s_nop 0
	global_load_dwordx4 v[214:217], v[214:215], off
	s_nop 0
	global_load_dwordx4 v[218:221], v[218:219], off
	s_nop 0
	global_load_dwordx4 v[222:225], v[222:223], off
	s_nop 0
	global_load_dwordx4 v[226:229], v[226:227], off
.Lmg_noload_g1024:
	ds_read_b128 v[236:239], v158
	ds_read_b128 v[244:247], v159 offset:18432
	ds_read_b128 v[248:251], v159 offset:23040
	ds_read_b128 v[240:243], v158 offset:4608
	s_waitcnt lgkmcnt(2)
	v_mfma_f32_32x32x16_bf16 v[50:65], v[236:239], v[244:247], v[50:65]
	s_waitcnt lgkmcnt(1)
	v_mfma_f32_32x32x16_bf16 v[34:49], v[236:239], v[248:251], v[34:49]
	ds_read_b128 v[236:239], v158 offset:32
	s_waitcnt lgkmcnt(1)
	v_mfma_f32_32x32x16_bf16 v[18:33], v[240:243], v[244:247], v[18:33]
	ds_read_b128 v[244:247], v159 offset:18464
	v_mfma_f32_32x32x16_bf16 v[2:17], v[240:243], v[248:251], v[2:17]
	ds_read_b128 v[248:251], v159 offset:23072
	ds_read_b128 v[240:243], v158 offset:4640
	s_waitcnt lgkmcnt(2)
	v_mfma_f32_32x32x16_bf16 v[50:65], v[236:239], v[244:247], v[50:65]
	s_waitcnt lgkmcnt(1)
	v_mfma_f32_32x32x16_bf16 v[34:49], v[236:239], v[248:251], v[34:49]
	ds_read_b128 v[236:239], v158 offset:64
	s_waitcnt lgkmcnt(1)
	v_mfma_f32_32x32x16_bf16 v[18:33], v[240:243], v[244:247], v[18:33]
	ds_read_b128 v[244:247], v159 offset:18496
	v_mfma_f32_32x32x16_bf16 v[2:17], v[240:243], v[248:251], v[2:17]
	ds_read_b128 v[248:251], v159 offset:23104
	ds_read_b128 v[240:243], v158 offset:4672
	s_waitcnt lgkmcnt(2)
	v_mfma_f32_32x32x16_bf16 v[50:65], v[236:239], v[244:247], v[50:65]
	s_waitcnt lgkmcnt(1)
	v_mfma_f32_32x32x16_bf16 v[34:49], v[236:239], v[248:251], v[34:49]
	ds_read_b128 v[236:239], v158 offset:96
	s_waitcnt lgkmcnt(1)
	v_mfma_f32_32x32x16_bf16 v[18:33], v[240:243], v[244:247], v[18:33]
	ds_read_b128 v[244:247], v159 offset:18528
	v_mfma_f32_32x32x16_bf16 v[2:17], v[240:243], v[248:251], v[2:17]
	ds_read_b128 v[248:251], v159 offset:23136
	ds_read_b128 v[240:243], v158 offset:4704
	s_waitcnt lgkmcnt(2)
	v_mfma_f32_32x32x16_bf16 v[50:65], v[236:239], v[244:247], v[50:65]
	s_waitcnt lgkmcnt(1)
	v_mfma_f32_32x32x16_bf16 v[34:49], v[236:239], v[248:251], v[34:49]
	s_waitcnt lgkmcnt(0)
	v_mfma_f32_32x32x16_bf16 v[18:33], v[240:243], v[244:247], v[18:33]
	v_mfma_f32_32x32x16_bf16 v[2:17], v[240:243], v[248:251], v[2:17]
	s_cbranch_scc1 .LBB0_106
	s_nop 15
	s_nop 6
	v_mul_f32_e32 v0, 0xbfb8aa3b, v50
	v_exp_f32_e32 v50, v0
	v_mul_f32_e32 v0, 0xbfb8aa3b, v51
	v_exp_f32_e32 v51, v0
	v_mul_f32_e32 v52, 0xbfb8aa3b, v52
	v_mul_f32_e32 v53, 0xbfb8aa3b, v53
	v_exp_f32_e32 v52, v52
	v_pk_add_f32 v[50:51], v[50:51], 1.0 op_sel_hi:[1,0]
	v_exp_f32_e32 v53, v53
	v_div_scale_f32 v0, s[4:5], v51, v51, 1.0
	v_rcp_f32_e32 v156, v0
	v_div_scale_f32 v158, vcc, 1.0, v51, 1.0
	v_pk_add_f32 v[52:53], v[52:53], 1.0 op_sel_hi:[1,0]
	v_fma_f32 v159, -v0, v156, 1.0
	v_fmac_f32_e32 v156, v159, v156
	v_mul_f32_e32 v159, v158, v156
	v_fma_f32 v160, -v0, v159, v158
	v_fmac_f32_e32 v159, v160, v156
	v_fma_f32 v0, -v0, v159, v158
	v_div_scale_f32 v158, s[4:5], v50, v50, 1.0
	v_rcp_f32_e32 v160, v158
	v_div_fmas_f32 v0, v0, v156, v159
	v_div_fixup_f32 v0, v0, v51, 1.0
	v_mul_f32_e32 v34, 0xbfb8aa3b, v34
	v_fma_f32 v51, -v158, v160, 1.0
	v_fmac_f32_e32 v160, v51, v160
	v_div_scale_f32 v51, vcc, 1.0, v50, 1.0
	v_mul_f32_e32 v156, v51, v160
	v_fma_f32 v159, -v158, v156, v51
	v_fmac_f32_e32 v156, v159, v160
	v_fma_f32 v51, -v158, v156, v51
	v_div_scale_f32 v158, s[4:5], v53, v53, 1.0
	v_rcp_f32_e32 v159, v158
	v_div_fmas_f32 v51, v51, v160, v156
	v_div_fixup_f32 v50, v51, v50, 1.0
	v_cvt_pk_bf16_f32 v0, v50, v0
	v_fma_f32 v50, -v158, v159, 1.0
	v_fmac_f32_e32 v159, v50, v159
	v_div_scale_f32 v50, vcc, 1.0, v53, 1.0
	v_mul_f32_e32 v51, v50, v159
	v_fma_f32 v156, -v158, v51, v50
	v_fmac_f32_e32 v51, v156, v159
	v_div_scale_f32 v156, s[4:5], v52, v52, 1.0
	v_fma_f32 v50, -v158, v51, v50
	v_rcp_f32_e32 v158, v156
	v_div_fmas_f32 v50, v50, v159, v51
	v_div_fixup_f32 v53, v50, v53, 1.0
	v_div_scale_f32 v159, vcc, 1.0, v52, 1.0
	v_fma_f32 v50, -v156, v158, 1.0
	v_fmac_f32_e32 v158, v50, v158
	v_mul_f32_e32 v160, v159, v158
	v_fma_f32 v50, -v156, v160, v159
	v_fmac_f32_e32 v160, v50, v158
	v_mul_f32_e32 v50, 0xbfb8aa3b, v54
	v_mul_f32_e32 v51, 0xbfb8aa3b, v55
	v_exp_f32_e32 v50, v50
	v_exp_f32_e32 v51, v51
	v_fma_f32 v54, -v156, v160, v159
	v_div_fmas_f32 v54, v54, v158, v160
	v_div_fixup_f32 v52, v54, v52, 1.0
	v_pk_add_f32 v[50:51], v[50:51], 1.0 op_sel_hi:[1,0]
	v_cvt_pk_bf16_f32 v52, v52, v53
	v_div_scale_f32 v55, s[4:5], v51, v51, 1.0
	v_rcp_f32_e32 v156, v55
	ds_write2st64_b32 v131, v0, v52 offset0:144 offset1:148
	v_div_scale_f32 v54, s[4:5], v50, v50, 1.0
	v_fma_f32 v0, -v55, v156, 1.0
	v_fmac_f32_e32 v156, v0, v156
	v_div_scale_f32 v0, vcc, 1.0, v51, 1.0
	v_mul_f32_e32 v52, v0, v156
	v_fma_f32 v53, -v55, v52, v0
	v_fmac_f32_e32 v52, v53, v156
	v_fma_f32 v0, -v55, v52, v0
	v_rcp_f32_e32 v55, v54
	v_div_fmas_f32 v0, v0, v156, v52
	v_mul_f32_e32 v52, 0xbfb8aa3b, v56
	v_mul_f32_e32 v53, 0xbfb8aa3b, v57
	v_div_fixup_f32 v0, v0, v51, 1.0
	v_fma_f32 v51, -v54, v55, 1.0
	v_exp_f32_e32 v52, v52
	v_exp_f32_e32 v53, v53
	v_fmac_f32_e32 v55, v51, v55
	v_div_scale_f32 v51, vcc, 1.0, v50, 1.0
	v_mul_f32_e32 v156, v51, v55
	v_fma_f32 v56, -v54, v156, v51
	v_fmac_f32_e32 v156, v56, v55
	v_pk_add_f32 v[52:53], v[52:53], 1.0 op_sel_hi:[1,0]
	v_fma_f32 v51, -v54, v156, v51
	v_div_scale_f32 v54, s[4:5], v53, v53, 1.0
	v_rcp_f32_e32 v56, v54
	v_div_fmas_f32 v51, v51, v55, v156
	v_div_fixup_f32 v50, v51, v50, 1.0
	v_cvt_pk_bf16_f32 v0, v50, v0
	v_fma_f32 v50, -v54, v56, 1.0
	v_fmac_f32_e32 v56, v50, v56
	v_div_scale_f32 v50, vcc, 1.0, v53, 1.0
	v_mul_f32_e32 v51, v50, v56
	v_fma_f32 v55, -v54, v51, v50
	v_fmac_f32_e32 v51, v55, v56
	v_fma_f32 v50, -v54, v51, v50
	v_div_scale_f32 v54, s[4:5], v52, v52, 1.0
	v_rcp_f32_e32 v55, v54
	v_div_fmas_f32 v50, v50, v56, v51
	v_div_fixup_f32 v53, v50, v53, 1.0
	v_div_scale_f32 v56, vcc, 1.0, v52, 1.0
	v_fma_f32 v50, -v54, v55, 1.0
	v_fmac_f32_e32 v55, v50, v55
	v_mul_f32_e32 v57, v56, v55
	v_fma_f32 v50, -v54, v57, v56
	v_fmac_f32_e32 v57, v50, v55
	v_mul_f32_e32 v50, 0xbfb8aa3b, v58
	v_mul_f32_e32 v51, 0xbfb8aa3b, v59
	v_exp_f32_e32 v50, v50
	v_exp_f32_e32 v51, v51
	v_fma_f32 v54, -v54, v57, v56
	v_div_fmas_f32 v54, v54, v55, v57
	v_div_fixup_f32 v52, v54, v52, 1.0
	v_pk_add_f32 v[50:51], v[50:51], 1.0 op_sel_hi:[1,0]
	v_cvt_pk_bf16_f32 v52, v52, v53
	v_div_scale_f32 v55, s[4:5], v51, v51, 1.0
	v_rcp_f32_e32 v56, v55
	ds_write2st64_b32 v131, v0, v52 offset0:152 offset1:156
	v_div_scale_f32 v54, s[4:5], v50, v50, 1.0
	v_fma_f32 v0, -v55, v56, 1.0
	v_fmac_f32_e32 v56, v0, v56
	v_div_scale_f32 v0, vcc, 1.0, v51, 1.0
	v_mul_f32_e32 v52, v0, v56
	v_fma_f32 v53, -v55, v52, v0
	v_fmac_f32_e32 v52, v53, v56
	v_fma_f32 v0, -v55, v52, v0
	v_rcp_f32_e32 v55, v54
	v_div_fmas_f32 v0, v0, v56, v52
	v_mul_f32_e32 v52, 0xbfb8aa3b, v60
	v_mul_f32_e32 v53, 0xbfb8aa3b, v61
	v_div_fixup_f32 v0, v0, v51, 1.0
	v_fma_f32 v51, -v54, v55, 1.0
	v_exp_f32_e32 v52, v52
	v_exp_f32_e32 v53, v53
	v_fmac_f32_e32 v55, v51, v55
	v_div_scale_f32 v51, vcc, 1.0, v50, 1.0
	v_mul_f32_e32 v56, v51, v55
	v_fma_f32 v57, -v54, v56, v51
	v_fmac_f32_e32 v56, v57, v55
	v_pk_add_f32 v[52:53], v[52:53], 1.0 op_sel_hi:[1,0]
	v_fma_f32 v51, -v54, v56, v51
	v_div_scale_f32 v54, s[4:5], v53, v53, 1.0
	v_rcp_f32_e32 v57, v54
	v_div_fmas_f32 v51, v51, v55, v56
	v_div_fixup_f32 v50, v51, v50, 1.0
	v_cvt_pk_bf16_f32 v0, v50, v0
	v_fma_f32 v50, -v54, v57, 1.0
	v_fmac_f32_e32 v57, v50, v57
	v_div_scale_f32 v50, vcc, 1.0, v53, 1.0
	v_mul_f32_e32 v51, v50, v57
	v_fma_f32 v55, -v54, v51, v50
	v_fmac_f32_e32 v51, v55, v57
	v_fma_f32 v50, -v54, v51, v50
	v_div_scale_f32 v54, s[4:5], v52, v52, 1.0
	v_rcp_f32_e32 v55, v54
	v_div_fmas_f32 v50, v50, v57, v51
	v_div_fixup_f32 v53, v50, v53, 1.0
	v_div_scale_f32 v56, vcc, 1.0, v52, 1.0
	v_fma_f32 v50, -v54, v55, 1.0
	v_fmac_f32_e32 v55, v50, v55
	v_mul_f32_e32 v57, v56, v55
	v_fma_f32 v50, -v54, v57, v56
	v_fmac_f32_e32 v57, v50, v55
	v_mul_f32_e32 v50, 0xbfb8aa3b, v62
	v_mul_f32_e32 v51, 0xbfb8aa3b, v63
	v_exp_f32_e32 v50, v50
	v_exp_f32_e32 v51, v51
	v_fma_f32 v54, -v54, v57, v56
	v_div_fmas_f32 v54, v54, v55, v57
	v_div_fixup_f32 v52, v54, v52, 1.0
	v_pk_add_f32 v[50:51], v[50:51], 1.0 op_sel_hi:[1,0]
	v_cvt_pk_bf16_f32 v52, v52, v53
	v_div_scale_f32 v55, s[4:5], v51, v51, 1.0
	v_rcp_f32_e32 v56, v55
	ds_write2st64_b32 v131, v0, v52 offset0:160 offset1:164
	v_div_scale_f32 v54, s[4:5], v50, v50, 1.0
	v_fma_f32 v0, -v55, v56, 1.0
	v_fmac_f32_e32 v56, v0, v56
	v_div_scale_f32 v0, vcc, 1.0, v51, 1.0
	v_mul_f32_e32 v52, v0, v56
	v_fma_f32 v53, -v55, v52, v0
	v_fmac_f32_e32 v52, v53, v56
	v_fma_f32 v0, -v55, v52, v0
	v_rcp_f32_e32 v55, v54
	v_div_fmas_f32 v0, v0, v56, v52
	v_mul_f32_e32 v52, 0xbfb8aa3b, v64
	v_mul_f32_e32 v53, 0xbfb8aa3b, v65
	v_div_fixup_f32 v0, v0, v51, 1.0
	v_fma_f32 v51, -v54, v55, 1.0
	v_exp_f32_e32 v52, v52
	v_exp_f32_e32 v53, v53
	v_fmac_f32_e32 v55, v51, v55
	v_div_scale_f32 v51, vcc, 1.0, v50, 1.0
	v_mul_f32_e32 v56, v51, v55
	v_fma_f32 v57, -v54, v56, v51
	v_fmac_f32_e32 v56, v57, v55
	v_pk_add_f32 v[52:53], v[52:53], 1.0 op_sel_hi:[1,0]
	v_fma_f32 v51, -v54, v56, v51
	v_div_scale_f32 v54, s[4:5], v53, v53, 1.0
	v_rcp_f32_e32 v57, v54
	v_div_fmas_f32 v51, v51, v55, v56
	v_div_fixup_f32 v50, v51, v50, 1.0
	v_cvt_pk_bf16_f32 v0, v50, v0
	v_fma_f32 v50, -v54, v57, 1.0
	v_fmac_f32_e32 v57, v50, v57
	v_div_scale_f32 v50, vcc, 1.0, v53, 1.0
	v_mul_f32_e32 v51, v50, v57
	v_fma_f32 v55, -v54, v51, v50
	v_fmac_f32_e32 v51, v55, v57
	v_fma_f32 v50, -v54, v51, v50
	v_div_scale_f32 v54, s[4:5], v52, v52, 1.0
	v_rcp_f32_e32 v55, v54
	v_div_fmas_f32 v50, v50, v57, v51
	v_mul_f32_e32 v35, 0xbfb8aa3b, v35
	v_exp_f32_e32 v34, v34
	v_fma_f32 v51, -v54, v55, 1.0
	v_fmac_f32_e32 v55, v51, v55
	v_div_scale_f32 v51, vcc, 1.0, v52, 1.0
	v_exp_f32_e32 v35, v35
	v_div_fixup_f32 v50, v50, v53, 1.0
	v_mul_f32_e32 v53, v51, v55
	v_fma_f32 v56, -v54, v53, v51
	v_fmac_f32_e32 v53, v56, v55
	v_fma_f32 v51, -v54, v53, v51
	v_pk_add_f32 v[34:35], v[34:35], 1.0 op_sel_hi:[1,0]
	v_div_fmas_f32 v51, v51, v55, v53
	v_div_scale_f32 v53, s[4:5], v35, v35, 1.0
	v_rcp_f32_e32 v54, v53
	v_div_fixup_f32 v51, v51, v52, 1.0
	v_cvt_pk_bf16_f32 v50, v51, v50
	ds_write2st64_b32 v131, v0, v50 offset0:168 offset1:172
	v_fma_f32 v0, -v53, v54, 1.0
	v_fmac_f32_e32 v54, v0, v54
	v_div_scale_f32 v0, vcc, 1.0, v35, 1.0
	v_mul_f32_e32 v50, v0, v54
	v_fma_f32 v51, -v53, v50, v0
	v_fmac_f32_e32 v50, v51, v54
	v_div_scale_f32 v51, s[4:5], v34, v34, 1.0
	v_rcp_f32_e32 v52, v51
	v_fma_f32 v0, -v53, v50, v0
	v_div_fmas_f32 v0, v0, v54, v50
	v_mul_f32_e32 v36, 0xbfb8aa3b, v36
	v_mul_f32_e32 v37, 0xbfb8aa3b, v37
	v_div_fixup_f32 v0, v0, v35, 1.0
	v_fma_f32 v35, -v51, v52, 1.0
	v_exp_f32_e32 v36, v36
	v_exp_f32_e32 v37, v37
	v_fmac_f32_e32 v52, v35, v52
	v_div_scale_f32 v35, vcc, 1.0, v34, 1.0
	v_mul_f32_e32 v50, v35, v52
	v_fma_f32 v53, -v51, v50, v35
	v_fmac_f32_e32 v50, v53, v52
	v_pk_add_f32 v[36:37], v[36:37], 1.0 op_sel_hi:[1,0]
	v_fma_f32 v35, -v51, v50, v35
	v_div_scale_f32 v51, s[4:5], v37, v37, 1.0
	v_rcp_f32_e32 v53, v51
	v_div_fmas_f32 v35, v35, v52, v50
	v_div_fixup_f32 v34, v35, v34, 1.0
	v_cvt_pk_bf16_f32 v0, v34, v0
	v_fma_f32 v34, -v51, v53, 1.0
	v_fmac_f32_e32 v53, v34, v53
	v_div_scale_f32 v34, vcc, 1.0, v37, 1.0
	v_mul_f32_e32 v35, v34, v53
	v_fma_f32 v50, -v51, v35, v34
	v_fmac_f32_e32 v35, v50, v53
	v_div_scale_f32 v50, s[4:5], v36, v36, 1.0
	v_fma_f32 v34, -v51, v35, v34
	v_rcp_f32_e32 v51, v50
	v_div_fmas_f32 v34, v34, v53, v35
	v_div_fixup_f32 v37, v34, v37, 1.0
	v_div_scale_f32 v52, vcc, 1.0, v36, 1.0
	v_fma_f32 v34, -v50, v51, 1.0
	v_fmac_f32_e32 v51, v34, v51
	v_mul_f32_e32 v53, v52, v51
	v_fma_f32 v34, -v50, v53, v52
	v_fmac_f32_e32 v53, v34, v51
	v_mul_f32_e32 v34, 0xbfb8aa3b, v38
	v_mul_f32_e32 v35, 0xbfb8aa3b, v39
	v_exp_f32_e32 v34, v34
	v_exp_f32_e32 v35, v35
	v_fma_f32 v38, -v50, v53, v52
	v_div_fmas_f32 v38, v38, v51, v53
	v_div_fixup_f32 v36, v38, v36, 1.0
	v_pk_add_f32 v[34:35], v[34:35], 1.0 op_sel_hi:[1,0]
	v_cvt_pk_bf16_f32 v36, v36, v37
	v_div_scale_f32 v39, s[4:5], v35, v35, 1.0
	v_rcp_f32_e32 v50, v39
	ds_write2st64_b32 v131, v0, v36 offset0:176 offset1:180
	v_div_scale_f32 v38, s[4:5], v34, v34, 1.0
	v_fma_f32 v0, -v39, v50, 1.0
	v_fmac_f32_e32 v50, v0, v50
	v_div_scale_f32 v0, vcc, 1.0, v35, 1.0
	v_mul_f32_e32 v36, v0, v50
	v_fma_f32 v37, -v39, v36, v0
	v_fmac_f32_e32 v36, v37, v50
	v_fma_f32 v0, -v39, v36, v0
	v_rcp_f32_e32 v39, v38
	v_div_fmas_f32 v0, v0, v50, v36
	v_mul_f32_e32 v36, 0xbfb8aa3b, v40
	v_mul_f32_e32 v37, 0xbfb8aa3b, v41
	v_div_fixup_f32 v0, v0, v35, 1.0
	v_fma_f32 v35, -v38, v39, 1.0
	v_exp_f32_e32 v36, v36
	v_exp_f32_e32 v37, v37
	v_fmac_f32_e32 v39, v35, v39
	v_div_scale_f32 v35, vcc, 1.0, v34, 1.0
	v_mul_f32_e32 v50, v35, v39
	v_fma_f32 v40, -v38, v50, v35
	v_fmac_f32_e32 v50, v40, v39
	v_pk_add_f32 v[36:37], v[36:37], 1.0 op_sel_hi:[1,0]
	v_fma_f32 v35, -v38, v50, v35
	v_div_scale_f32 v38, s[4:5], v37, v37, 1.0
	v_rcp_f32_e32 v40, v38
	v_div_fmas_f32 v35, v35, v39, v50
	v_div_fixup_f32 v34, v35, v34, 1.0
	v_cvt_pk_bf16_f32 v0, v34, v0
	v_fma_f32 v34, -v38, v40, 1.0
	v_fmac_f32_e32 v40, v34, v40
	v_div_scale_f32 v34, vcc, 1.0, v37, 1.0
	v_mul_f32_e32 v35, v34, v40
	v_fma_f32 v39, -v38, v35, v34
	v_fmac_f32_e32 v35, v39, v40
	v_fma_f32 v34, -v38, v35, v34
	v_div_scale_f32 v38, s[4:5], v36, v36, 1.0
	v_rcp_f32_e32 v39, v38
	v_div_fmas_f32 v34, v34, v40, v35
	v_div_fixup_f32 v37, v34, v37, 1.0
	v_div_scale_f32 v40, vcc, 1.0, v36, 1.0
	v_fma_f32 v34, -v38, v39, 1.0
	v_fmac_f32_e32 v39, v34, v39
	v_mul_f32_e32 v41, v40, v39
	v_fma_f32 v34, -v38, v41, v40
	v_fmac_f32_e32 v41, v34, v39
	v_mul_f32_e32 v34, 0xbfb8aa3b, v42
	v_mul_f32_e32 v35, 0xbfb8aa3b, v43
	v_exp_f32_e32 v34, v34
	v_exp_f32_e32 v35, v35
	v_fma_f32 v38, -v38, v41, v40
	v_div_fmas_f32 v38, v38, v39, v41
	v_div_fixup_f32 v36, v38, v36, 1.0
	v_pk_add_f32 v[34:35], v[34:35], 1.0 op_sel_hi:[1,0]
	v_cvt_pk_bf16_f32 v36, v36, v37
	v_div_scale_f32 v39, s[4:5], v35, v35, 1.0
	v_rcp_f32_e32 v40, v39
	ds_write2st64_b32 v131, v0, v36 offset0:184 offset1:188
	v_div_scale_f32 v38, s[4:5], v34, v34, 1.0
	v_fma_f32 v0, -v39, v40, 1.0
	v_fmac_f32_e32 v40, v0, v40
	v_div_scale_f32 v0, vcc, 1.0, v35, 1.0
	v_mul_f32_e32 v36, v0, v40
	v_fma_f32 v37, -v39, v36, v0
	v_fmac_f32_e32 v36, v37, v40
	v_fma_f32 v0, -v39, v36, v0
	v_rcp_f32_e32 v39, v38
	v_div_fmas_f32 v0, v0, v40, v36
	v_mul_f32_e32 v36, 0xbfb8aa3b, v44
	v_mul_f32_e32 v37, 0xbfb8aa3b, v45
	v_div_fixup_f32 v0, v0, v35, 1.0
	v_fma_f32 v35, -v38, v39, 1.0
	v_exp_f32_e32 v36, v36
	v_exp_f32_e32 v37, v37
	v_fmac_f32_e32 v39, v35, v39
	v_div_scale_f32 v35, vcc, 1.0, v34, 1.0
	v_mul_f32_e32 v40, v35, v39
	v_fma_f32 v41, -v38, v40, v35
	v_fmac_f32_e32 v40, v41, v39
	v_pk_add_f32 v[36:37], v[36:37], 1.0 op_sel_hi:[1,0]
	v_fma_f32 v35, -v38, v40, v35
	v_div_scale_f32 v38, s[4:5], v37, v37, 1.0
	v_rcp_f32_e32 v41, v38
	v_div_fmas_f32 v35, v35, v39, v40
	v_div_fixup_f32 v34, v35, v34, 1.0
	v_cvt_pk_bf16_f32 v0, v34, v0
	v_fma_f32 v34, -v38, v41, 1.0
	v_fmac_f32_e32 v41, v34, v41
	v_div_scale_f32 v34, vcc, 1.0, v37, 1.0
	v_mul_f32_e32 v35, v34, v41
	v_fma_f32 v39, -v38, v35, v34
	v_fmac_f32_e32 v35, v39, v41
	v_fma_f32 v34, -v38, v35, v34
	v_div_scale_f32 v38, s[4:5], v36, v36, 1.0
	v_rcp_f32_e32 v39, v38
	v_div_fmas_f32 v34, v34, v41, v35
	v_div_fixup_f32 v37, v34, v37, 1.0
	v_div_scale_f32 v40, vcc, 1.0, v36, 1.0
	v_fma_f32 v34, -v38, v39, 1.0
	v_fmac_f32_e32 v39, v34, v39
	v_mul_f32_e32 v41, v40, v39
	v_fma_f32 v34, -v38, v41, v40
	v_fmac_f32_e32 v41, v34, v39
	v_mul_f32_e32 v34, 0xbfb8aa3b, v46
	v_mul_f32_e32 v35, 0xbfb8aa3b, v47
	v_exp_f32_e32 v34, v34
	v_exp_f32_e32 v35, v35
	v_fma_f32 v38, -v38, v41, v40
	v_div_fmas_f32 v38, v38, v39, v41
	v_div_fixup_f32 v36, v38, v36, 1.0
	v_pk_add_f32 v[34:35], v[34:35], 1.0 op_sel_hi:[1,0]
	v_cvt_pk_bf16_f32 v36, v36, v37
	v_div_scale_f32 v39, s[4:5], v35, v35, 1.0
	v_rcp_f32_e32 v40, v39
	ds_write2st64_b32 v131, v0, v36 offset0:192 offset1:196
	v_div_scale_f32 v38, s[4:5], v34, v34, 1.0
	v_fma_f32 v0, -v39, v40, 1.0
	v_fmac_f32_e32 v40, v0, v40
	v_div_scale_f32 v0, vcc, 1.0, v35, 1.0
	v_mul_f32_e32 v36, v0, v40
	v_fma_f32 v37, -v39, v36, v0
	v_fmac_f32_e32 v36, v37, v40
	v_fma_f32 v0, -v39, v36, v0
	v_rcp_f32_e32 v39, v38
	v_div_fmas_f32 v0, v0, v40, v36
	v_mul_f32_e32 v36, 0xbfb8aa3b, v48
	v_mul_f32_e32 v37, 0xbfb8aa3b, v49
	v_div_fixup_f32 v0, v0, v35, 1.0
	v_fma_f32 v35, -v38, v39, 1.0
	v_exp_f32_e32 v36, v36
	v_exp_f32_e32 v37, v37
	v_fmac_f32_e32 v39, v35, v39
	v_div_scale_f32 v35, vcc, 1.0, v34, 1.0
	v_mul_f32_e32 v40, v35, v39
	v_fma_f32 v41, -v38, v40, v35
	v_fmac_f32_e32 v40, v41, v39
	v_pk_add_f32 v[36:37], v[36:37], 1.0 op_sel_hi:[1,0]
	v_fma_f32 v35, -v38, v40, v35
	v_div_scale_f32 v38, s[4:5], v37, v37, 1.0
	v_rcp_f32_e32 v41, v38
	v_div_fmas_f32 v35, v35, v39, v40
	v_div_fixup_f32 v34, v35, v34, 1.0
	v_cvt_pk_bf16_f32 v0, v34, v0
	v_fma_f32 v34, -v38, v41, 1.0
	v_fmac_f32_e32 v41, v34, v41
	v_div_scale_f32 v34, vcc, 1.0, v37, 1.0
	v_mul_f32_e32 v35, v34, v41
	v_fma_f32 v39, -v38, v35, v34
	v_fmac_f32_e32 v35, v39, v41
	v_fma_f32 v34, -v38, v35, v34
	v_div_scale_f32 v38, s[4:5], v36, v36, 1.0
	v_rcp_f32_e32 v39, v38
	v_div_fmas_f32 v34, v34, v41, v35
	v_mul_f32_e32 v18, 0xbfb8aa3b, v18
	v_mul_f32_e32 v19, 0xbfb8aa3b, v19
	v_fma_f32 v35, -v38, v39, 1.0
	v_fmac_f32_e32 v39, v35, v39
	v_div_scale_f32 v35, vcc, 1.0, v36, 1.0
	v_exp_f32_e32 v18, v18
	v_exp_f32_e32 v19, v19
	v_div_fixup_f32 v34, v34, v37, 1.0
	v_mul_f32_e32 v37, v35, v39
	v_fma_f32 v40, -v38, v37, v35
	v_fmac_f32_e32 v37, v40, v39
	v_fma_f32 v35, -v38, v37, v35
	v_pk_add_f32 v[18:19], v[18:19], 1.0 op_sel_hi:[1,0]
	v_div_fmas_f32 v35, v35, v39, v37
	v_div_scale_f32 v37, s[4:5], v19, v19, 1.0
	v_rcp_f32_e32 v38, v37
	v_div_fixup_f32 v35, v35, v36, 1.0
	v_cvt_pk_bf16_f32 v34, v35, v34
	ds_write2st64_b32 v131, v0, v34 offset0:200 offset1:204
	v_fma_f32 v0, -v37, v38, 1.0
	v_fmac_f32_e32 v38, v0, v38
	v_div_scale_f32 v0, vcc, 1.0, v19, 1.0
	v_mul_f32_e32 v34, v0, v38
	v_fma_f32 v35, -v37, v34, v0
	v_fmac_f32_e32 v34, v35, v38
	v_div_scale_f32 v35, s[4:5], v18, v18, 1.0
	v_rcp_f32_e32 v36, v35
	v_fma_f32 v0, -v37, v34, v0
	v_div_fmas_f32 v0, v0, v38, v34
	v_mul_f32_e32 v20, 0xbfb8aa3b, v20
	v_mul_f32_e32 v21, 0xbfb8aa3b, v21
	v_div_fixup_f32 v0, v0, v19, 1.0
	v_fma_f32 v19, -v35, v36, 1.0
	v_exp_f32_e32 v20, v20
	v_exp_f32_e32 v21, v21
	v_fmac_f32_e32 v36, v19, v36
	v_div_scale_f32 v19, vcc, 1.0, v18, 1.0
	v_mul_f32_e32 v34, v19, v36
	v_fma_f32 v37, -v35, v34, v19
	v_fmac_f32_e32 v34, v37, v36
	v_pk_add_f32 v[20:21], v[20:21], 1.0 op_sel_hi:[1,0]
	v_fma_f32 v19, -v35, v34, v19
	v_div_scale_f32 v35, s[4:5], v21, v21, 1.0
	v_rcp_f32_e32 v37, v35
	v_div_fmas_f32 v19, v19, v36, v34
	v_div_fixup_f32 v18, v19, v18, 1.0
	v_cvt_pk_bf16_f32 v0, v18, v0
	v_fma_f32 v18, -v35, v37, 1.0
	v_fmac_f32_e32 v37, v18, v37
	v_div_scale_f32 v18, vcc, 1.0, v21, 1.0
	v_mul_f32_e32 v19, v18, v37
	v_fma_f32 v34, -v35, v19, v18
	v_fmac_f32_e32 v19, v34, v37
	v_div_scale_f32 v34, s[4:5], v20, v20, 1.0
	v_fma_f32 v18, -v35, v19, v18
	v_rcp_f32_e32 v35, v34
	v_div_fmas_f32 v18, v18, v37, v19
	v_div_fixup_f32 v21, v18, v21, 1.0
	v_div_scale_f32 v36, vcc, 1.0, v20, 1.0
	v_fma_f32 v18, -v34, v35, 1.0
	v_fmac_f32_e32 v35, v18, v35
	v_mul_f32_e32 v37, v36, v35
	v_fma_f32 v18, -v34, v37, v36
	v_fmac_f32_e32 v37, v18, v35
	v_mul_f32_e32 v18, 0xbfb8aa3b, v22
	v_mul_f32_e32 v19, 0xbfb8aa3b, v23
	v_exp_f32_e32 v18, v18
	v_exp_f32_e32 v19, v19
	v_fma_f32 v22, -v34, v37, v36
	v_div_fmas_f32 v22, v22, v35, v37
	v_div_fixup_f32 v20, v22, v20, 1.0
	v_pk_add_f32 v[18:19], v[18:19], 1.0 op_sel_hi:[1,0]
	v_cvt_pk_bf16_f32 v20, v20, v21
	v_div_scale_f32 v23, s[4:5], v19, v19, 1.0
	v_rcp_f32_e32 v34, v23
	ds_write2st64_b32 v131, v0, v20 offset0:208 offset1:212
	v_div_scale_f32 v22, s[4:5], v18, v18, 1.0
	v_fma_f32 v0, -v23, v34, 1.0
	v_fmac_f32_e32 v34, v0, v34
	v_div_scale_f32 v0, vcc, 1.0, v19, 1.0
	v_mul_f32_e32 v20, v0, v34
	v_fma_f32 v21, -v23, v20, v0
	v_fmac_f32_e32 v20, v21, v34
	v_fma_f32 v0, -v23, v20, v0
	v_rcp_f32_e32 v23, v22
	v_div_fmas_f32 v0, v0, v34, v20
	v_mul_f32_e32 v20, 0xbfb8aa3b, v24
	v_mul_f32_e32 v21, 0xbfb8aa3b, v25
	v_div_fixup_f32 v0, v0, v19, 1.0
	v_fma_f32 v19, -v22, v23, 1.0
	v_exp_f32_e32 v20, v20
	v_exp_f32_e32 v21, v21
	v_fmac_f32_e32 v23, v19, v23
	v_div_scale_f32 v19, vcc, 1.0, v18, 1.0
	v_mul_f32_e32 v34, v19, v23
	v_fma_f32 v24, -v22, v34, v19
	v_fmac_f32_e32 v34, v24, v23
	v_pk_add_f32 v[20:21], v[20:21], 1.0 op_sel_hi:[1,0]
	v_fma_f32 v19, -v22, v34, v19
	v_div_scale_f32 v22, s[4:5], v21, v21, 1.0
	v_rcp_f32_e32 v24, v22
	v_div_fmas_f32 v19, v19, v23, v34
	v_div_fixup_f32 v18, v19, v18, 1.0
	v_cvt_pk_bf16_f32 v0, v18, v0
	v_fma_f32 v18, -v22, v24, 1.0
	v_fmac_f32_e32 v24, v18, v24
	v_div_scale_f32 v18, vcc, 1.0, v21, 1.0
	v_mul_f32_e32 v19, v18, v24
	v_fma_f32 v23, -v22, v19, v18
	v_fmac_f32_e32 v19, v23, v24
	v_fma_f32 v18, -v22, v19, v18
	v_div_scale_f32 v22, s[4:5], v20, v20, 1.0
	v_rcp_f32_e32 v23, v22
	v_div_fmas_f32 v18, v18, v24, v19
	v_div_fixup_f32 v21, v18, v21, 1.0
	v_div_scale_f32 v24, vcc, 1.0, v20, 1.0
	v_fma_f32 v18, -v22, v23, 1.0
	v_fmac_f32_e32 v23, v18, v23
	v_mul_f32_e32 v25, v24, v23
	v_fma_f32 v18, -v22, v25, v24
	v_fmac_f32_e32 v25, v18, v23
	v_mul_f32_e32 v18, 0xbfb8aa3b, v26
	v_mul_f32_e32 v19, 0xbfb8aa3b, v27
	v_exp_f32_e32 v18, v18
	v_exp_f32_e32 v19, v19
	v_fma_f32 v22, -v22, v25, v24
	v_div_fmas_f32 v22, v22, v23, v25
	v_div_fixup_f32 v20, v22, v20, 1.0
	v_pk_add_f32 v[18:19], v[18:19], 1.0 op_sel_hi:[1,0]
	v_cvt_pk_bf16_f32 v20, v20, v21
	v_div_scale_f32 v23, s[4:5], v19, v19, 1.0
	v_rcp_f32_e32 v24, v23
	ds_write2st64_b32 v131, v0, v20 offset0:216 offset1:220
	v_div_scale_f32 v22, s[4:5], v18, v18, 1.0
	v_fma_f32 v0, -v23, v24, 1.0
	v_fmac_f32_e32 v24, v0, v24
	v_div_scale_f32 v0, vcc, 1.0, v19, 1.0
	v_mul_f32_e32 v20, v0, v24
	v_fma_f32 v21, -v23, v20, v0
	v_fmac_f32_e32 v20, v21, v24
	v_fma_f32 v0, -v23, v20, v0
	v_rcp_f32_e32 v23, v22
	v_div_fmas_f32 v0, v0, v24, v20
	v_mul_f32_e32 v20, 0xbfb8aa3b, v28
	v_mul_f32_e32 v21, 0xbfb8aa3b, v29
	v_div_fixup_f32 v0, v0, v19, 1.0
	v_fma_f32 v19, -v22, v23, 1.0
	v_exp_f32_e32 v20, v20
	v_exp_f32_e32 v21, v21
	v_fmac_f32_e32 v23, v19, v23
	v_div_scale_f32 v19, vcc, 1.0, v18, 1.0
	v_mul_f32_e32 v24, v19, v23
	v_fma_f32 v25, -v22, v24, v19
	v_fmac_f32_e32 v24, v25, v23
	v_pk_add_f32 v[20:21], v[20:21], 1.0 op_sel_hi:[1,0]
	v_fma_f32 v19, -v22, v24, v19
	v_div_scale_f32 v22, s[4:5], v21, v21, 1.0
	v_rcp_f32_e32 v25, v22
	v_div_fmas_f32 v19, v19, v23, v24
	v_div_fixup_f32 v18, v19, v18, 1.0
	v_cvt_pk_bf16_f32 v0, v18, v0
	v_fma_f32 v18, -v22, v25, 1.0
	v_fmac_f32_e32 v25, v18, v25
	v_div_scale_f32 v18, vcc, 1.0, v21, 1.0
	v_mul_f32_e32 v19, v18, v25
	v_fma_f32 v23, -v22, v19, v18
	v_fmac_f32_e32 v19, v23, v25
	v_fma_f32 v18, -v22, v19, v18
	v_div_scale_f32 v22, s[4:5], v20, v20, 1.0
	v_rcp_f32_e32 v23, v22
	v_div_fmas_f32 v18, v18, v25, v19
	v_div_fixup_f32 v21, v18, v21, 1.0
	v_div_scale_f32 v24, vcc, 1.0, v20, 1.0
	v_fma_f32 v18, -v22, v23, 1.0
	v_fmac_f32_e32 v23, v18, v23
	v_mul_f32_e32 v25, v24, v23
	v_fma_f32 v18, -v22, v25, v24
	v_fmac_f32_e32 v25, v18, v23
	v_mul_f32_e32 v18, 0xbfb8aa3b, v30
	v_mul_f32_e32 v19, 0xbfb8aa3b, v31
	v_exp_f32_e32 v18, v18
	v_exp_f32_e32 v19, v19
	v_fma_f32 v22, -v22, v25, v24
	v_div_fmas_f32 v22, v22, v23, v25
	v_div_fixup_f32 v20, v22, v20, 1.0
	v_pk_add_f32 v[18:19], v[18:19], 1.0 op_sel_hi:[1,0]
	v_cvt_pk_bf16_f32 v20, v20, v21
	v_div_scale_f32 v23, s[4:5], v19, v19, 1.0
	v_rcp_f32_e32 v24, v23
	ds_write2st64_b32 v131, v0, v20 offset0:224 offset1:228
	v_div_scale_f32 v22, s[4:5], v18, v18, 1.0
	v_fma_f32 v0, -v23, v24, 1.0
	v_fmac_f32_e32 v24, v0, v24
	v_div_scale_f32 v0, vcc, 1.0, v19, 1.0
	v_mul_f32_e32 v20, v0, v24
	v_fma_f32 v21, -v23, v20, v0
	v_fmac_f32_e32 v20, v21, v24
	v_fma_f32 v0, -v23, v20, v0
	v_rcp_f32_e32 v23, v22
	v_div_fmas_f32 v0, v0, v24, v20
	v_mul_f32_e32 v20, 0xbfb8aa3b, v32
	v_mul_f32_e32 v21, 0xbfb8aa3b, v33
	v_div_fixup_f32 v0, v0, v19, 1.0
	v_fma_f32 v19, -v22, v23, 1.0
	v_exp_f32_e32 v20, v20
	v_exp_f32_e32 v21, v21
	v_fmac_f32_e32 v23, v19, v23
	v_div_scale_f32 v19, vcc, 1.0, v18, 1.0
	v_mul_f32_e32 v24, v19, v23
	v_fma_f32 v25, -v22, v24, v19
	v_fmac_f32_e32 v24, v25, v23
	v_pk_add_f32 v[20:21], v[20:21], 1.0 op_sel_hi:[1,0]
	v_fma_f32 v19, -v22, v24, v19
	v_div_scale_f32 v22, s[4:5], v21, v21, 1.0
	v_rcp_f32_e32 v25, v22
	v_div_fmas_f32 v19, v19, v23, v24
	v_div_fixup_f32 v18, v19, v18, 1.0
	v_cvt_pk_bf16_f32 v0, v18, v0
	v_fma_f32 v18, -v22, v25, 1.0
	v_fmac_f32_e32 v25, v18, v25
	v_div_scale_f32 v18, vcc, 1.0, v21, 1.0
	v_mul_f32_e32 v19, v18, v25
	v_fma_f32 v23, -v22, v19, v18
	v_fmac_f32_e32 v19, v23, v25
	v_fma_f32 v18, -v22, v19, v18
	v_div_scale_f32 v22, s[4:5], v20, v20, 1.0
	v_rcp_f32_e32 v23, v22
	v_div_fmas_f32 v18, v18, v25, v19
	v_mul_f32_e32 v2, 0xbfb8aa3b, v2
	v_mul_f32_e32 v3, 0xbfb8aa3b, v3
	v_fma_f32 v19, -v22, v23, 1.0
	v_fmac_f32_e32 v23, v19, v23
	v_div_scale_f32 v19, vcc, 1.0, v20, 1.0
	v_exp_f32_e32 v2, v2
	v_exp_f32_e32 v3, v3
	v_div_fixup_f32 v18, v18, v21, 1.0
	v_mul_f32_e32 v21, v19, v23
	v_fma_f32 v24, -v22, v21, v19
	v_fmac_f32_e32 v21, v24, v23
	v_fma_f32 v19, -v22, v21, v19
	v_pk_add_f32 v[2:3], v[2:3], 1.0 op_sel_hi:[1,0]
	v_div_fmas_f32 v19, v19, v23, v21
	v_div_scale_f32 v21, s[4:5], v3, v3, 1.0
	v_rcp_f32_e32 v22, v21
	v_div_fixup_f32 v19, v19, v20, 1.0
	v_cvt_pk_bf16_f32 v18, v19, v18
	ds_write2st64_b32 v131, v0, v18 offset0:232 offset1:236
	v_fma_f32 v0, -v21, v22, 1.0
	v_fmac_f32_e32 v22, v0, v22
	v_div_scale_f32 v0, vcc, 1.0, v3, 1.0
	v_mul_f32_e32 v18, v0, v22
	v_fma_f32 v19, -v21, v18, v0
	v_fmac_f32_e32 v18, v19, v22
	v_div_scale_f32 v19, s[4:5], v2, v2, 1.0
	v_rcp_f32_e32 v20, v19
	v_fma_f32 v0, -v21, v18, v0
	v_div_fmas_f32 v0, v0, v22, v18
	v_mul_f32_e32 v4, 0xbfb8aa3b, v4
	v_mul_f32_e32 v5, 0xbfb8aa3b, v5
	v_div_fixup_f32 v0, v0, v3, 1.0
	v_fma_f32 v3, -v19, v20, 1.0
	v_exp_f32_e32 v4, v4
	v_exp_f32_e32 v5, v5
	v_fmac_f32_e32 v20, v3, v20
	v_div_scale_f32 v3, vcc, 1.0, v2, 1.0
	v_mul_f32_e32 v18, v3, v20
	v_fma_f32 v21, -v19, v18, v3
	v_fmac_f32_e32 v18, v21, v20
	v_pk_add_f32 v[4:5], v[4:5], 1.0 op_sel_hi:[1,0]
	v_fma_f32 v3, -v19, v18, v3
	v_div_scale_f32 v19, s[4:5], v5, v5, 1.0
	v_rcp_f32_e32 v21, v19
	v_div_fmas_f32 v3, v3, v20, v18
	v_div_fixup_f32 v2, v3, v2, 1.0
	v_cvt_pk_bf16_f32 v0, v2, v0
	v_fma_f32 v2, -v19, v21, 1.0
	v_fmac_f32_e32 v21, v2, v21
	v_div_scale_f32 v2, vcc, 1.0, v5, 1.0
	v_mul_f32_e32 v3, v2, v21
	v_fma_f32 v18, -v19, v3, v2
	v_fmac_f32_e32 v3, v18, v21
	v_div_scale_f32 v18, s[4:5], v4, v4, 1.0
	v_fma_f32 v2, -v19, v3, v2
	v_rcp_f32_e32 v19, v18
	v_div_fmas_f32 v2, v2, v21, v3
	v_div_fixup_f32 v5, v2, v5, 1.0
	v_div_scale_f32 v20, vcc, 1.0, v4, 1.0
	v_fma_f32 v2, -v18, v19, 1.0
	v_fmac_f32_e32 v19, v2, v19
	v_mul_f32_e32 v21, v20, v19
	v_fma_f32 v2, -v18, v21, v20
	v_fmac_f32_e32 v21, v2, v19
	v_mul_f32_e32 v2, 0xbfb8aa3b, v6
	v_mul_f32_e32 v3, 0xbfb8aa3b, v7
	v_exp_f32_e32 v2, v2
	v_exp_f32_e32 v3, v3
	v_fma_f32 v6, -v18, v21, v20
	v_div_fmas_f32 v6, v6, v19, v21
	v_div_fixup_f32 v4, v6, v4, 1.0
	v_pk_add_f32 v[2:3], v[2:3], 1.0 op_sel_hi:[1,0]
	v_cvt_pk_bf16_f32 v4, v4, v5
	v_div_scale_f32 v7, s[4:5], v3, v3, 1.0
	v_rcp_f32_e32 v18, v7
	ds_write2st64_b32 v131, v0, v4 offset0:240 offset1:244
	v_div_scale_f32 v6, s[4:5], v2, v2, 1.0
	v_fma_f32 v0, -v7, v18, 1.0
	v_fmac_f32_e32 v18, v0, v18
	v_div_scale_f32 v0, vcc, 1.0, v3, 1.0
	v_mul_f32_e32 v4, v0, v18
	v_fma_f32 v5, -v7, v4, v0
	v_fmac_f32_e32 v4, v5, v18
	v_fma_f32 v0, -v7, v4, v0
	v_rcp_f32_e32 v7, v6
	v_div_fmas_f32 v0, v0, v18, v4
	v_mul_f32_e32 v4, 0xbfb8aa3b, v8
	v_mul_f32_e32 v5, 0xbfb8aa3b, v9
	v_div_fixup_f32 v0, v0, v3, 1.0
	v_fma_f32 v3, -v6, v7, 1.0
	v_exp_f32_e32 v4, v4
	v_exp_f32_e32 v5, v5
	v_fmac_f32_e32 v7, v3, v7
	v_div_scale_f32 v3, vcc, 1.0, v2, 1.0
	v_mul_f32_e32 v18, v3, v7
	v_fma_f32 v8, -v6, v18, v3
	v_fmac_f32_e32 v18, v8, v7
	v_pk_add_f32 v[4:5], v[4:5], 1.0 op_sel_hi:[1,0]
	v_fma_f32 v3, -v6, v18, v3
	v_div_scale_f32 v6, s[4:5], v5, v5, 1.0
	v_rcp_f32_e32 v8, v6
	v_div_fmas_f32 v3, v3, v7, v18
	v_div_fixup_f32 v2, v3, v2, 1.0
	v_cvt_pk_bf16_f32 v0, v2, v0
	v_fma_f32 v2, -v6, v8, 1.0
	v_fmac_f32_e32 v8, v2, v8
	v_div_scale_f32 v2, vcc, 1.0, v5, 1.0
	v_mul_f32_e32 v3, v2, v8
	v_fma_f32 v7, -v6, v3, v2
	v_fmac_f32_e32 v3, v7, v8
	v_fma_f32 v2, -v6, v3, v2
	v_div_scale_f32 v6, s[4:5], v4, v4, 1.0
	v_rcp_f32_e32 v7, v6
	v_div_fmas_f32 v2, v2, v8, v3
	v_div_fixup_f32 v5, v2, v5, 1.0
	v_div_scale_f32 v8, vcc, 1.0, v4, 1.0
	v_fma_f32 v2, -v6, v7, 1.0
	v_fmac_f32_e32 v7, v2, v7
	v_mul_f32_e32 v9, v8, v7
	v_fma_f32 v2, -v6, v9, v8
	v_fmac_f32_e32 v9, v2, v7
	v_mul_f32_e32 v2, 0xbfb8aa3b, v10
	v_mul_f32_e32 v3, 0xbfb8aa3b, v11
	v_exp_f32_e32 v2, v2
	v_exp_f32_e32 v3, v3
	v_fma_f32 v6, -v6, v9, v8
	v_div_fmas_f32 v6, v6, v7, v9
	v_div_fixup_f32 v4, v6, v4, 1.0
	v_pk_add_f32 v[2:3], v[2:3], 1.0 op_sel_hi:[1,0]
	v_cvt_pk_bf16_f32 v4, v4, v5
	v_div_scale_f32 v7, s[4:5], v3, v3, 1.0
	v_rcp_f32_e32 v8, v7
	ds_write2st64_b32 v131, v0, v4 offset0:248 offset1:252
	v_div_scale_f32 v6, s[4:5], v2, v2, 1.0
	v_fma_f32 v0, -v7, v8, 1.0
	v_fmac_f32_e32 v8, v0, v8
	v_div_scale_f32 v0, vcc, 1.0, v3, 1.0
	v_mul_f32_e32 v4, v0, v8
	v_fma_f32 v5, -v7, v4, v0
	v_fmac_f32_e32 v4, v5, v8
	v_fma_f32 v0, -v7, v4, v0
	v_rcp_f32_e32 v7, v6
	v_div_fmas_f32 v0, v0, v8, v4
	v_mul_f32_e32 v4, 0xbfb8aa3b, v12
	v_mul_f32_e32 v5, 0xbfb8aa3b, v13
	v_div_fixup_f32 v0, v0, v3, 1.0
	v_fma_f32 v3, -v6, v7, 1.0
	v_exp_f32_e32 v4, v4
	v_exp_f32_e32 v5, v5
	v_fmac_f32_e32 v7, v3, v7
	v_div_scale_f32 v3, vcc, 1.0, v2, 1.0
	v_mul_f32_e32 v8, v3, v7
	v_fma_f32 v9, -v6, v8, v3
	v_fmac_f32_e32 v8, v9, v7
	v_pk_add_f32 v[4:5], v[4:5], 1.0 op_sel_hi:[1,0]
	v_fma_f32 v3, -v6, v8, v3
	v_div_scale_f32 v6, s[4:5], v5, v5, 1.0
	v_rcp_f32_e32 v9, v6
	v_div_fmas_f32 v3, v3, v7, v8
	v_div_fixup_f32 v2, v3, v2, 1.0
	v_cvt_pk_bf16_f32 v0, v2, v0
	v_fma_f32 v2, -v6, v9, 1.0
	v_fmac_f32_e32 v9, v2, v9
	v_div_scale_f32 v2, vcc, 1.0, v5, 1.0
	v_mul_f32_e32 v3, v2, v9
	v_fma_f32 v7, -v6, v3, v2
	v_fmac_f32_e32 v3, v7, v9
	v_fma_f32 v2, -v6, v3, v2
	v_div_scale_f32 v6, s[4:5], v4, v4, 1.0
	v_rcp_f32_e32 v7, v6
	v_div_fmas_f32 v2, v2, v9, v3
	v_div_fixup_f32 v5, v2, v5, 1.0
	v_div_scale_f32 v8, vcc, 1.0, v4, 1.0
	v_fma_f32 v2, -v6, v7, 1.0
	v_fmac_f32_e32 v7, v2, v7
	v_mul_f32_e32 v9, v8, v7
	v_fma_f32 v2, -v6, v9, v8
	v_fmac_f32_e32 v9, v2, v7
	v_mul_f32_e32 v2, 0xbfb8aa3b, v14
	v_mul_f32_e32 v3, 0xbfb8aa3b, v15
	v_exp_f32_e32 v2, v2
	v_exp_f32_e32 v3, v3
	v_fma_f32 v6, -v6, v9, v8
	v_div_fmas_f32 v6, v6, v7, v9
	v_div_fixup_f32 v4, v6, v4, 1.0
	v_pk_add_f32 v[2:3], v[2:3], 1.0 op_sel_hi:[1,0]
	v_cvt_pk_bf16_f32 v4, v4, v5
	v_div_scale_f32 v7, s[4:5], v3, v3, 1.0
	v_rcp_f32_e32 v8, v7
	ds_write2st64_b32 v135, v0, v4 offset0:112 offset1:116
	v_div_scale_f32 v6, s[4:5], v2, v2, 1.0
	v_fma_f32 v0, -v7, v8, 1.0
	v_fmac_f32_e32 v8, v0, v8
	v_div_scale_f32 v0, vcc, 1.0, v3, 1.0
	v_mul_f32_e32 v4, v0, v8
	v_fma_f32 v5, -v7, v4, v0
	v_fmac_f32_e32 v4, v5, v8
	v_fma_f32 v0, -v7, v4, v0
	v_rcp_f32_e32 v7, v6
	v_div_fmas_f32 v0, v0, v8, v4
	v_mul_f32_e32 v4, 0xbfb8aa3b, v16
	v_mul_f32_e32 v5, 0xbfb8aa3b, v17
	v_div_fixup_f32 v0, v0, v3, 1.0
	v_fma_f32 v3, -v6, v7, 1.0
	v_exp_f32_e32 v4, v4
	v_exp_f32_e32 v5, v5
	v_fmac_f32_e32 v7, v3, v7
	v_div_scale_f32 v3, vcc, 1.0, v2, 1.0
	v_mul_f32_e32 v8, v3, v7
	v_fma_f32 v9, -v6, v8, v3
	v_fmac_f32_e32 v8, v9, v7
	v_pk_add_f32 v[4:5], v[4:5], 1.0 op_sel_hi:[1,0]
	v_fma_f32 v3, -v6, v8, v3
	v_div_scale_f32 v6, s[4:5], v5, v5, 1.0
	v_rcp_f32_e32 v9, v6
	v_div_fmas_f32 v3, v3, v7, v8
	v_div_fixup_f32 v2, v3, v2, 1.0
	v_cvt_pk_bf16_f32 v0, v2, v0
	v_fma_f32 v2, -v6, v9, 1.0
	v_fmac_f32_e32 v9, v2, v9
	v_div_scale_f32 v2, vcc, 1.0, v5, 1.0
	v_mul_f32_e32 v3, v2, v9
	v_fma_f32 v7, -v6, v3, v2
	v_fmac_f32_e32 v3, v7, v9
	v_fma_f32 v2, -v6, v3, v2
	v_div_scale_f32 v6, s[4:5], v4, v4, 1.0
	v_rcp_f32_e32 v7, v6
	v_div_fmas_f32 v2, v2, v9, v3
	v_div_fixup_f32 v2, v2, v5, 1.0
	s_or_b32 s4, s6, s13
	v_fma_f32 v3, -v6, v7, 1.0
	v_fmac_f32_e32 v7, v3, v7
	v_div_scale_f32 v3, vcc, 1.0, v4, 1.0
	v_mul_f32_e32 v5, v3, v7
	v_fma_f32 v8, -v6, v5, v3
	v_fmac_f32_e32 v5, v8, v7
	v_fma_f32 v3, -v6, v5, v3
	v_div_fmas_f32 v3, v3, v7, v5
	v_div_fixup_f32 v3, v3, v4, 1.0
	v_cvt_pk_bf16_f32 v2, v3, v2
	v_mov_b32_e32 v3, v133
	ds_write2st64_b32 v135, v0, v2 offset0:120 offset1:124
	s_mov_b32 s15, 0xfffffc0
	v_lshlrev_b32_e32 v0, 3, v3
	v_ashrrev_i32_e32 v4, 3, v3
	v_and_b32_e32 v156, 56, v0
	v_add_u32_e32 v0, 0x100, v3
	v_mul_lo_u32 v174, v4, s34
	v_lshlrev_b32_e32 v175, 9, v4
	v_ashrrev_i32_e32 v5, 3, v0
	v_add_u32_e32 v6, 0x200, v3
	v_mul_lo_u32 v4, v4, s21
	v_ashrrev_i32_e32 v6, 3, v6
	v_add_u32_e32 v7, 0x300, v3
	v_add_lshl_u32 v182, v4, v156, 1
	v_mul_lo_u32 v4, v5, s21
	v_ashrrev_i32_e32 v7, 3, v7
	v_add_lshl_u32 v183, v4, v156, 1
	v_mul_lo_u32 v4, v6, s21
	v_add_lshl_u32 v213, v4, v156, 1
	v_mul_lo_u32 v4, v7, s21
	v_and_b32_e32 v2, 31, v3
	v_add_lshl_u32 v214, v4, v156, 1
	v_lshrrev_b32_e32 v4, 1, v3
	s_add_u32 s4, s42, s4
	v_mul_lo_u32 v176, v5, s34
	v_lshlrev_b32_e32 v177, 9, v5
	v_and_or_b32 v5, v4, s15, v2
	v_and_b32_e32 v2, 16, v4
	s_addc_u32 s5, s43, 0
	s_lshl_b32 s6, s12, 10
	v_mad_u64_u32 v[158:159], s[16:17], v5, s37, v[2:3]
	v_and_b32_e32 v3, 0x5f, v3
	s_add_u32 s6, s9, s6
	v_mul_lo_u32 v178, v6, s34
	v_lshlrev_b32_e32 v179, 9, v6
	v_mul_lo_u32 v180, v7, s34
	v_lshlrev_b32_e32 v181, 9, v7
	v_mad_u32_u24 v159, v3, s37, v2
	v_mov_b32_e32 v2, 0
	s_mov_b32 s14, 1
	s_addc_u32 s7, s10, 0
	v_or_b32_e32 v162, v174, v156
	v_or_b32_e32 v160, v175, v156
	v_or_b32_e32 v0, v176, v156
	v_or_b32_e32 v164, v177, v156
	v_or_b32_e32 v166, v178, v156
	v_or_b32_e32 v168, v179, v156
	v_or_b32_e32 v170, v180, v156
	v_or_b32_e32 v172, v181, v156
	v_mov_b32_e32 v3, v2
	v_mov_b32_e32 v4, v2
	v_mov_b32_e32 v5, v2
	v_mov_b32_e32 v6, v2
	v_mov_b32_e32 v7, v2
	v_mov_b32_e32 v8, v2
	v_mov_b32_e32 v9, v2
	v_mov_b32_e32 v10, v2
	v_mov_b32_e32 v11, v2
	v_mov_b32_e32 v12, v2
	v_mov_b32_e32 v13, v2
	v_mov_b32_e32 v14, v2
	v_mov_b32_e32 v15, v2
	v_mov_b32_e32 v16, v2
	v_mov_b32_e32 v17, v2
	v_mov_b32_e32 v18, v2
	v_mov_b32_e32 v19, v2
	v_mov_b32_e32 v20, v2
	v_mov_b32_e32 v21, v2
	v_mov_b32_e32 v22, v2
	v_mov_b32_e32 v23, v2
	v_mov_b32_e32 v24, v2
	v_mov_b32_e32 v25, v2
	v_mov_b32_e32 v26, v2
	v_mov_b32_e32 v27, v2
	v_mov_b32_e32 v28, v2
	v_mov_b32_e32 v29, v2
	v_mov_b32_e32 v30, v2
	v_mov_b32_e32 v31, v2
	v_mov_b32_e32 v32, v2
	v_mov_b32_e32 v33, v2
	v_mov_b32_e32 v34, v2
	v_mov_b32_e32 v35, v2
	v_mov_b32_e32 v36, v2
	v_mov_b32_e32 v37, v2
	v_mov_b32_e32 v38, v2
	v_mov_b32_e32 v39, v2
	v_mov_b32_e32 v40, v2
	v_mov_b32_e32 v41, v2
	v_mov_b32_e32 v42, v2
	v_mov_b32_e32 v43, v2
	v_mov_b32_e32 v44, v2
	v_mov_b32_e32 v45, v2
	v_mov_b32_e32 v46, v2
	v_mov_b32_e32 v47, v2
	v_mov_b32_e32 v48, v2
	v_mov_b32_e32 v49, v2
	v_mov_b32_e32 v50, v2
	v_mov_b32_e32 v51, v2
	v_mov_b32_e32 v52, v2
	v_mov_b32_e32 v53, v2
	v_mov_b32_e32 v54, v2
	v_mov_b32_e32 v55, v2
	v_mov_b32_e32 v56, v2
	v_mov_b32_e32 v57, v2
	v_mov_b32_e32 v58, v2
	v_mov_b32_e32 v59, v2
	v_mov_b32_e32 v60, v2
	v_mov_b32_e32 v61, v2
	v_mov_b32_e32 v62, v2
	v_mov_b32_e32 v63, v2
	v_mov_b32_e32 v64, v2
	v_mov_b32_e32 v65, v2
	v_mov_b32_e32 v163, v1
	v_mov_b32_e32 v169, v1
	v_mov_b32_e32 v165, v1
	v_mov_b32_e32 v161, v1
	v_mov_b32_e32 v167, v1
	v_mov_b32_e32 v171, v1
	v_lshl_add_u64 v[216:217], v[0:1], 1, s[6:7]
	v_mov_b32_e32 v173, v1
	v_lshl_add_u64 v[218:219], v[162:163], 1, s[6:7]
	v_lshl_add_u64 v[224:225], v[168:169], 1, s[4:5]
	v_lshl_add_u64 v[220:221], v[164:165], 1, s[4:5]
	v_lshl_add_u64 v[168:169], v[160:161], 1, s[4:5]
	v_lshl_add_u64 v[222:223], v[166:167], 1, s[6:7]
	v_lshl_add_u64 v[228:229], v[170:171], 1, s[6:7]
	v_lshl_add_u64 v[172:173], v[172:173], 1, s[4:5]
	global_load_dwordx4 v[160:163], v[216:217], off
	global_load_dwordx4 v[164:167], v[218:219], off
	s_nop 0
	global_load_dwordx4 v[168:171], v[168:169], off
	s_nop 0
	global_load_dwordx4 v[216:219], v[220:221], off
	s_nop 0
	global_load_dwordx4 v[220:223], v[222:223], off
	s_nop 0
	global_load_dwordx4 v[224:227], v[224:225], off
	s_nop 0
	global_load_dwordx4 v[228:231], v[228:229], off
	s_nop 0
	global_load_dwordx4 v[232:235], v[172:173], off
.LBB0_108:
	s_waitcnt lgkmcnt(0)
	s_barrier
	s_waitcnt vmcnt(6)
	ds_write_b128 v182, v[164:167]
	s_waitcnt vmcnt(5)
	ds_write_b128 v182, v[168:171] offset:18432
	ds_write_b128 v183, v[160:163]
	s_waitcnt vmcnt(4)
	ds_write_b128 v183, v[216:219] offset:18432
	s_waitcnt vmcnt(3)
	ds_write_b128 v213, v[220:223]
	s_waitcnt vmcnt(2)
	ds_write_b128 v213, v[224:227] offset:18432
	s_waitcnt vmcnt(1)
	ds_write_b128 v214, v[228:231]
	s_waitcnt vmcnt(0)
	ds_write_b128 v214, v[232:235] offset:18432
	s_waitcnt lgkmcnt(0)
	s_barrier
	s_min_u32 s15, s14, 7
	s_add_i32 s14, s14, 1
	s_cmp_lg_u32 s14, 9
	s_cbranch_scc0 .Lmg_noload_u512
	v_lshl_or_b32 v161, s15, 6, v156
	v_or_b32_e32 v162, v161, v174
	v_or_b32_e32 v160, v161, v175
	v_or_b32_e32 v0, v161, v176
	v_or_b32_e32 v172, v161, v181
	v_or_b32_e32 v164, v161, v177
	v_or_b32_e32 v166, v161, v178
	v_or_b32_e32 v168, v161, v179
	v_or_b32_e32 v170, v161, v180
	v_mov_b32_e32 v163, v1
	v_mov_b32_e32 v169, v1
	v_mov_b32_e32 v165, v1
	v_mov_b32_e32 v161, v1
	v_mov_b32_e32 v167, v1
	v_mov_b32_e32 v171, v1
	v_lshl_add_u64 v[216:217], v[0:1], 1, s[6:7]
	v_mov_b32_e32 v173, v1
	v_lshl_add_u64 v[218:219], v[162:163], 1, s[6:7]
	v_lshl_add_u64 v[224:225], v[168:169], 1, s[4:5]
	v_lshl_add_u64 v[220:221], v[164:165], 1, s[4:5]
	v_lshl_add_u64 v[168:169], v[160:161], 1, s[4:5]
	v_lshl_add_u64 v[222:223], v[166:167], 1, s[6:7]
	v_lshl_add_u64 v[228:229], v[170:171], 1, s[6:7]
	v_lshl_add_u64 v[172:173], v[172:173], 1, s[4:5]
	global_load_dwordx4 v[160:163], v[216:217], off
	global_load_dwordx4 v[164:167], v[218:219], off
	s_nop 0
	global_load_dwordx4 v[168:171], v[168:169], off
	s_nop 0
	global_load_dwordx4 v[216:219], v[220:221], off
	s_nop 0
	global_load_dwordx4 v[220:223], v[222:223], off
	s_nop 0
	global_load_dwordx4 v[224:227], v[224:225], off
	s_nop 0
	global_load_dwordx4 v[228:231], v[228:229], off
	s_nop 0
	global_load_dwordx4 v[232:235], v[172:173], off
.Lmg_noload_u512:
	ds_read_b128 v[236:239], v158
	ds_read_b128 v[244:247], v159 offset:18432
	ds_read_b128 v[248:251], v159 offset:23040
	ds_read_b128 v[240:243], v158 offset:4608
	s_waitcnt lgkmcnt(2)
	v_mfma_f32_32x32x16_bf16 v[50:65], v[236:239], v[244:247], v[50:65]
	s_waitcnt lgkmcnt(1)
	v_mfma_f32_32x32x16_bf16 v[34:49], v[236:239], v[248:251], v[34:49]
	ds_read_b128 v[236:239], v158 offset:32
	s_waitcnt lgkmcnt(1)
	v_mfma_f32_32x32x16_bf16 v[18:33], v[240:243], v[244:247], v[18:33]
	ds_read_b128 v[244:247], v159 offset:18464
	v_mfma_f32_32x32x16_bf16 v[2:17], v[240:243], v[248:251], v[2:17]
	ds_read_b128 v[248:251], v159 offset:23072
	ds_read_b128 v[240:243], v158 offset:4640
	s_waitcnt lgkmcnt(2)
	v_mfma_f32_32x32x16_bf16 v[50:65], v[236:239], v[244:247], v[50:65]
	s_waitcnt lgkmcnt(1)
	v_mfma_f32_32x32x16_bf16 v[34:49], v[236:239], v[248:251], v[34:49]
	ds_read_b128 v[236:239], v158 offset:64
	s_waitcnt lgkmcnt(1)
	v_mfma_f32_32x32x16_bf16 v[18:33], v[240:243], v[244:247], v[18:33]
	ds_read_b128 v[244:247], v159 offset:18496
	v_mfma_f32_32x32x16_bf16 v[2:17], v[240:243], v[248:251], v[2:17]
	ds_read_b128 v[248:251], v159 offset:23104
	ds_read_b128 v[240:243], v158 offset:4672
	s_waitcnt lgkmcnt(2)
	v_mfma_f32_32x32x16_bf16 v[50:65], v[236:239], v[244:247], v[50:65]
	s_waitcnt lgkmcnt(1)
	v_mfma_f32_32x32x16_bf16 v[34:49], v[236:239], v[248:251], v[34:49]
	ds_read_b128 v[236:239], v158 offset:96
	s_waitcnt lgkmcnt(1)
	v_mfma_f32_32x32x16_bf16 v[18:33], v[240:243], v[244:247], v[18:33]
	ds_read_b128 v[244:247], v159 offset:18528
	v_mfma_f32_32x32x16_bf16 v[2:17], v[240:243], v[248:251], v[2:17]
	ds_read_b128 v[248:251], v159 offset:23136
	ds_read_b128 v[240:243], v158 offset:4704
	s_waitcnt lgkmcnt(2)
	v_mfma_f32_32x32x16_bf16 v[50:65], v[236:239], v[244:247], v[50:65]
	s_waitcnt lgkmcnt(1)
	v_mfma_f32_32x32x16_bf16 v[34:49], v[236:239], v[248:251], v[34:49]
	s_waitcnt lgkmcnt(0)
	v_mfma_f32_32x32x16_bf16 v[18:33], v[240:243], v[244:247], v[18:33]
	v_mfma_f32_32x32x16_bf16 v[2:17], v[240:243], v[248:251], v[2:17]
	s_cbranch_scc1 .LBB0_108
	s_nop 15
	ds_read2st64_b32 v[158:159], v131 offset0:144 offset1:148
	s_add_i32 s12, s12, 1
	s_cmp_lg_u32 s12, 3
	s_waitcnt lgkmcnt(0)
	v_lshlrev_b32_e32 v160, 16, v158
	v_and_b32_e32 v161, 0xffff0000, v158
	v_pk_fma_f32 v[128:129], v[50:51], v[160:161], v[128:129]
	v_lshlrev_b32_e32 v50, 16, v159
	v_and_b32_e32 v51, 0xffff0000, v159
	v_pk_fma_f32 v[126:127], v[52:53], v[50:51], v[126:127]
	ds_read2st64_b32 v[50:51], v131 offset0:152 offset1:156
	s_waitcnt lgkmcnt(0)
	v_lshlrev_b32_e32 v52, 16, v50
	v_and_b32_e32 v53, 0xffff0000, v50
	v_lshlrev_b32_e32 v50, 16, v51
	v_and_b32_e32 v51, 0xffff0000, v51
	v_pk_fma_f32 v[118:119], v[56:57], v[50:51], v[118:119]
	ds_read2st64_b32 v[50:51], v131 offset0:160 offset1:164
	v_pk_fma_f32 v[122:123], v[54:55], v[52:53], v[122:123]
	s_waitcnt lgkmcnt(0)
	v_lshlrev_b32_e32 v52, 16, v50
	v_and_b32_e32 v53, 0xffff0000, v50
	v_lshlrev_b32_e32 v50, 16, v51
	v_and_b32_e32 v51, 0xffff0000, v51
	v_pk_fma_f32 v[110:111], v[60:61], v[50:51], v[110:111]
	ds_read2st64_b32 v[50:51], v131 offset0:168 offset1:172
	v_pk_fma_f32 v[114:115], v[58:59], v[52:53], v[114:115]
	s_waitcnt lgkmcnt(0)
	v_lshlrev_b32_e32 v52, 16, v50
	v_and_b32_e32 v53, 0xffff0000, v50
	v_lshlrev_b32_e32 v50, 16, v51
	v_and_b32_e32 v51, 0xffff0000, v51
	v_pk_fma_f32 v[100:101], v[64:65], v[50:51], v[100:101]
	ds_read2st64_b32 v[50:51], v131 offset0:176 offset1:180
	v_pk_fma_f32 v[106:107], v[62:63], v[52:53], v[106:107]
	s_waitcnt lgkmcnt(0)
	v_lshlrev_b32_e32 v52, 16, v50
	v_and_b32_e32 v53, 0xffff0000, v50
	v_pk_fma_f32 v[124:125], v[34:35], v[52:53], v[124:125]
	v_lshlrev_b32_e32 v34, 16, v51
	v_and_b32_e32 v35, 0xffff0000, v51
	v_pk_fma_f32 v[120:121], v[36:37], v[34:35], v[120:121]
	ds_read2st64_b32 v[34:35], v131 offset0:184 offset1:188
	s_waitcnt lgkmcnt(0)
	v_lshlrev_b32_e32 v36, 16, v34
	v_and_b32_e32 v37, 0xffff0000, v34
	v_lshlrev_b32_e32 v34, 16, v35
	v_and_b32_e32 v35, 0xffff0000, v35
	v_pk_fma_f32 v[112:113], v[40:41], v[34:35], v[112:113]
	ds_read2st64_b32 v[34:35], v131 offset0:192 offset1:196
	v_pk_fma_f32 v[116:117], v[38:39], v[36:37], v[116:117]
	s_waitcnt lgkmcnt(0)
	v_lshlrev_b32_e32 v36, 16, v34
	v_and_b32_e32 v37, 0xffff0000, v34
	v_lshlrev_b32_e32 v34, 16, v35
	v_and_b32_e32 v35, 0xffff0000, v35
	v_pk_fma_f32 v[104:105], v[44:45], v[34:35], v[104:105]
	ds_read2st64_b32 v[34:35], v131 offset0:200 offset1:204
	v_pk_fma_f32 v[108:109], v[42:43], v[36:37], v[108:109]
	s_waitcnt lgkmcnt(0)
	v_lshlrev_b32_e32 v36, 16, v34
	v_and_b32_e32 v37, 0xffff0000, v34
	v_lshlrev_b32_e32 v34, 16, v35
	v_and_b32_e32 v35, 0xffff0000, v35
	v_pk_fma_f32 v[98:99], v[48:49], v[34:35], v[98:99]
	ds_read2st64_b32 v[34:35], v131 offset0:208 offset1:212
	v_pk_fma_f32 v[102:103], v[46:47], v[36:37], v[102:103]
	s_waitcnt lgkmcnt(0)
	v_lshlrev_b32_e32 v36, 16, v34
	v_and_b32_e32 v37, 0xffff0000, v34
	v_pk_fma_f32 v[96:97], v[18:19], v[36:37], v[96:97]
	v_lshlrev_b32_e32 v18, 16, v35
	v_and_b32_e32 v19, 0xffff0000, v35
	v_pk_fma_f32 v[94:95], v[20:21], v[18:19], v[94:95]
	ds_read2st64_b32 v[18:19], v131 offset0:216 offset1:220
	s_waitcnt lgkmcnt(0)
	v_lshlrev_b32_e32 v20, 16, v18
	v_and_b32_e32 v21, 0xffff0000, v18
	v_lshlrev_b32_e32 v18, 16, v19
	v_and_b32_e32 v19, 0xffff0000, v19
	v_pk_fma_f32 v[86:87], v[24:25], v[18:19], v[86:87]
	ds_read2st64_b32 v[18:19], v131 offset0:224 offset1:228
	v_pk_fma_f32 v[90:91], v[22:23], v[20:21], v[90:91]
	s_waitcnt lgkmcnt(0)
	v_lshlrev_b32_e32 v20, 16, v18
	v_and_b32_e32 v21, 0xffff0000, v18
	v_lshlrev_b32_e32 v18, 16, v19
	v_and_b32_e32 v19, 0xffff0000, v19
	v_pk_fma_f32 v[78:79], v[28:29], v[18:19], v[78:79]
	ds_read2st64_b32 v[18:19], v131 offset0:232 offset1:236
	v_pk_fma_f32 v[82:83], v[26:27], v[20:21], v[82:83]
	s_waitcnt lgkmcnt(0)
	v_lshlrev_b32_e32 v20, 16, v18
	v_and_b32_e32 v21, 0xffff0000, v18
	v_lshlrev_b32_e32 v18, 16, v19
	v_and_b32_e32 v19, 0xffff0000, v19
	v_pk_fma_f32 v[68:69], v[32:33], v[18:19], v[68:69]
	ds_read2st64_b32 v[18:19], v131 offset0:240 offset1:244
	v_pk_fma_f32 v[74:75], v[30:31], v[20:21], v[74:75]
	s_waitcnt lgkmcnt(0)
	v_lshlrev_b32_e32 v20, 16, v18
	v_and_b32_e32 v21, 0xffff0000, v18
	v_pk_fma_f32 v[92:93], v[2:3], v[20:21], v[92:93]
	v_lshlrev_b32_e32 v2, 16, v19
	v_and_b32_e32 v3, 0xffff0000, v19
	v_pk_fma_f32 v[88:89], v[4:5], v[2:3], v[88:89]
	ds_read2st64_b32 v[2:3], v131 offset0:248 offset1:252
	s_waitcnt lgkmcnt(0)
	v_lshlrev_b32_e32 v4, 16, v2
	v_and_b32_e32 v5, 0xffff0000, v2
	v_lshlrev_b32_e32 v2, 16, v3
	v_and_b32_e32 v3, 0xffff0000, v3
	v_pk_fma_f32 v[80:81], v[8:9], v[2:3], v[80:81]
	ds_read2st64_b32 v[2:3], v135 offset0:112 offset1:116
	v_pk_fma_f32 v[84:85], v[6:7], v[4:5], v[84:85]
	s_waitcnt lgkmcnt(0)
	v_lshlrev_b32_e32 v4, 16, v2
	v_and_b32_e32 v5, 0xffff0000, v2
	v_lshlrev_b32_e32 v2, 16, v3
	v_and_b32_e32 v3, 0xffff0000, v3
	v_pk_fma_f32 v[72:73], v[12:13], v[2:3], v[72:73]
	ds_read2st64_b32 v[2:3], v135 offset0:120 offset1:124
	v_pk_fma_f32 v[76:77], v[10:11], v[4:5], v[76:77]
	s_waitcnt lgkmcnt(0)
	v_lshlrev_b32_e32 v4, 16, v2
	v_and_b32_e32 v5, 0xffff0000, v2
	v_lshlrev_b32_e32 v2, 16, v3
	v_and_b32_e32 v3, 0xffff0000, v3
	v_pk_fma_f32 v[70:71], v[14:15], v[4:5], v[70:71]
	v_pk_fma_f32 v[66:67], v[16:17], v[2:3], v[66:67]
	s_cbranch_scc1 .LBB0_105
	v_mov_b32_e32 v0, v133
	v_mov_b32_e32 v2, v133
	s_nop 0
	v_and_b32_e32 v3, 64, v2
	v_and_b32_e32 v5, 31, v0
	v_ashrrev_i32_e32 v2, 1, v2
	v_lshrrev_b32_e32 v0, 3, v0
	v_and_b32_e32 v2, 0xffffffc0, v2
	v_and_or_b32 v0, v0, 4, s96
	v_add_u32_e32 v4, v0, v2
	v_or3_b32 v0, v5, v3, s8
	v_lshlrev_b32_e32 v0, 1, v0
	v_ashrrev_i32_e32 v5, 31, v4
	v_lshl_add_u64 v[2:3], s[88:89], 0, v[0:1]
	v_lshlrev_b64 v[6:7], 11, v[4:5]
	v_cvt_pk_bf16_f32 v0, v128, s0
	v_lshl_add_u64 v[6:7], v[2:3], 0, v[6:7]
	global_store_short v[6:7], v0, off
	v_cvt_pk_bf16_f32 v0, v124, s0
	global_store_short v[6:7], v0, off offset:64
	v_or_b32_e32 v6, 1, v4
	v_ashrrev_i32_e32 v7, 31, v6
	v_lshlrev_b64 v[6:7], 11, v[6:7]
	v_cvt_pk_bf16_f32 v0, v129, s0
	v_lshl_add_u64 v[6:7], v[2:3], 0, v[6:7]
	global_store_short v[6:7], v0, off
	v_cvt_pk_bf16_f32 v0, v125, s0
	global_store_short v[6:7], v0, off offset:64
	v_or_b32_e32 v6, 2, v4
	v_ashrrev_i32_e32 v7, 31, v6
	v_lshlrev_b64 v[6:7], 11, v[6:7]
	v_cvt_pk_bf16_f32 v0, v126, s0
	v_lshl_add_u64 v[6:7], v[2:3], 0, v[6:7]
	global_store_short v[6:7], v0, off
	v_cvt_pk_bf16_f32 v0, v120, s0
	global_store_short v[6:7], v0, off offset:64
	v_or_b32_e32 v6, 3, v4
	v_ashrrev_i32_e32 v7, 31, v6
	v_lshlrev_b64 v[6:7], 11, v[6:7]
	v_cvt_pk_bf16_f32 v0, v127, s0
	v_lshl_add_u64 v[6:7], v[2:3], 0, v[6:7]
	global_store_short v[6:7], v0, off
	v_cvt_pk_bf16_f32 v0, v121, s0
	global_store_short v[6:7], v0, off offset:64
	v_or_b32_e32 v6, 8, v4
	v_ashrrev_i32_e32 v7, 31, v6
	v_lshlrev_b64 v[6:7], 11, v[6:7]
	v_cvt_pk_bf16_f32 v0, v122, s0
	v_lshl_add_u64 v[6:7], v[2:3], 0, v[6:7]
	global_store_short v[6:7], v0, off
	v_cvt_pk_bf16_f32 v0, v116, s0
	global_store_short v[6:7], v0, off offset:64
	v_or_b32_e32 v6, 9, v4
	v_ashrrev_i32_e32 v7, 31, v6
	v_lshlrev_b64 v[6:7], 11, v[6:7]
	v_cvt_pk_bf16_f32 v0, v123, s0
	v_lshl_add_u64 v[6:7], v[2:3], 0, v[6:7]
	global_store_short v[6:7], v0, off
	v_cvt_pk_bf16_f32 v0, v117, s0
	global_store_short v[6:7], v0, off offset:64
	v_or_b32_e32 v6, 10, v4
	v_ashrrev_i32_e32 v7, 31, v6
	v_lshlrev_b64 v[6:7], 11, v[6:7]
	v_cvt_pk_bf16_f32 v0, v118, s0
	v_lshl_add_u64 v[6:7], v[2:3], 0, v[6:7]
	global_store_short v[6:7], v0, off
	v_cvt_pk_bf16_f32 v0, v112, s0
	global_store_short v[6:7], v0, off offset:64
	v_or_b32_e32 v6, 11, v4
	v_ashrrev_i32_e32 v7, 31, v6
	v_lshlrev_b64 v[6:7], 11, v[6:7]
	v_cvt_pk_bf16_f32 v0, v119, s0
	v_lshl_add_u64 v[6:7], v[2:3], 0, v[6:7]
	global_store_short v[6:7], v0, off
	v_cvt_pk_bf16_f32 v0, v113, s0
	global_store_short v[6:7], v0, off offset:64
	v_or_b32_e32 v6, 16, v4
	v_ashrrev_i32_e32 v7, 31, v6
	v_lshlrev_b64 v[6:7], 11, v[6:7]
	v_cvt_pk_bf16_f32 v0, v114, s0
	v_lshl_add_u64 v[6:7], v[2:3], 0, v[6:7]
	global_store_short v[6:7], v0, off
	v_cvt_pk_bf16_f32 v0, v108, s0
	global_store_short v[6:7], v0, off offset:64
	v_or_b32_e32 v6, 17, v4
	v_ashrrev_i32_e32 v7, 31, v6
	v_lshlrev_b64 v[6:7], 11, v[6:7]
	v_cvt_pk_bf16_f32 v0, v115, s0
	v_lshl_add_u64 v[6:7], v[2:3], 0, v[6:7]
	global_store_short v[6:7], v0, off
	v_cvt_pk_bf16_f32 v0, v109, s0
	global_store_short v[6:7], v0, off offset:64
	v_or_b32_e32 v6, 18, v4
	v_ashrrev_i32_e32 v7, 31, v6
	v_lshlrev_b64 v[6:7], 11, v[6:7]
	v_cvt_pk_bf16_f32 v0, v110, s0
	v_lshl_add_u64 v[6:7], v[2:3], 0, v[6:7]
	global_store_short v[6:7], v0, off
	v_cvt_pk_bf16_f32 v0, v104, s0
	global_store_short v[6:7], v0, off offset:64
	v_or_b32_e32 v6, 19, v4
	v_ashrrev_i32_e32 v7, 31, v6
	v_lshlrev_b64 v[6:7], 11, v[6:7]
	v_cvt_pk_bf16_f32 v0, v111, s0
	v_lshl_add_u64 v[6:7], v[2:3], 0, v[6:7]
	global_store_short v[6:7], v0, off
	v_cvt_pk_bf16_f32 v0, v105, s0
	global_store_short v[6:7], v0, off offset:64
	v_or_b32_e32 v6, 24, v4
	v_ashrrev_i32_e32 v7, 31, v6
	v_lshlrev_b64 v[6:7], 11, v[6:7]
	v_cvt_pk_bf16_f32 v0, v106, s0
	v_lshl_add_u64 v[6:7], v[2:3], 0, v[6:7]
	global_store_short v[6:7], v0, off
	v_cvt_pk_bf16_f32 v0, v102, s0
	global_store_short v[6:7], v0, off offset:64
	v_or_b32_e32 v6, 25, v4
	v_ashrrev_i32_e32 v7, 31, v6
	v_lshlrev_b64 v[6:7], 11, v[6:7]
	v_cvt_pk_bf16_f32 v0, v107, s0
	v_lshl_add_u64 v[6:7], v[2:3], 0, v[6:7]
	global_store_short v[6:7], v0, off
	v_cvt_pk_bf16_f32 v0, v103, s0
	global_store_short v[6:7], v0, off offset:64
	v_or_b32_e32 v6, 26, v4
	v_ashrrev_i32_e32 v7, 31, v6
	v_lshlrev_b64 v[6:7], 11, v[6:7]
	v_cvt_pk_bf16_f32 v0, v100, s0
	v_lshl_add_u64 v[6:7], v[2:3], 0, v[6:7]
	global_store_short v[6:7], v0, off
	v_cvt_pk_bf16_f32 v0, v98, s0
	global_store_short v[6:7], v0, off offset:64
	v_or_b32_e32 v6, 27, v4
	v_ashrrev_i32_e32 v7, 31, v6
	v_lshlrev_b64 v[6:7], 11, v[6:7]
	v_cvt_pk_bf16_f32 v0, v101, s0
	v_lshl_add_u64 v[6:7], v[2:3], 0, v[6:7]
	global_store_short v[6:7], v0, off
	v_cvt_pk_bf16_f32 v0, v99, s0
	global_store_short v[6:7], v0, off offset:64
	v_or_b32_e32 v6, 32, v4
	v_ashrrev_i32_e32 v7, 31, v6
	v_lshlrev_b64 v[6:7], 11, v[6:7]
	v_cvt_pk_bf16_f32 v0, v96, s0
	v_lshl_add_u64 v[6:7], v[2:3], 0, v[6:7]
	global_store_short v[6:7], v0, off
	v_cvt_pk_bf16_f32 v0, v92, s0
	global_store_short v[6:7], v0, off offset:64
	v_or_b32_e32 v6, 33, v4
	v_ashrrev_i32_e32 v7, 31, v6
	v_lshlrev_b64 v[6:7], 11, v[6:7]
	v_cvt_pk_bf16_f32 v0, v97, s0
	v_lshl_add_u64 v[6:7], v[2:3], 0, v[6:7]
	global_store_short v[6:7], v0, off
	v_cvt_pk_bf16_f32 v0, v93, s0
	global_store_short v[6:7], v0, off offset:64
	v_or_b32_e32 v6, 34, v4
	v_ashrrev_i32_e32 v7, 31, v6
	v_lshlrev_b64 v[6:7], 11, v[6:7]
	v_cvt_pk_bf16_f32 v0, v94, s0
	v_lshl_add_u64 v[6:7], v[2:3], 0, v[6:7]
	global_store_short v[6:7], v0, off
	v_cvt_pk_bf16_f32 v0, v88, s0
	global_store_short v[6:7], v0, off offset:64
	v_or_b32_e32 v6, 35, v4
	v_ashrrev_i32_e32 v7, 31, v6
	v_lshlrev_b64 v[6:7], 11, v[6:7]
	v_cvt_pk_bf16_f32 v0, v95, s0
	v_lshl_add_u64 v[6:7], v[2:3], 0, v[6:7]
	global_store_short v[6:7], v0, off
	v_cvt_pk_bf16_f32 v0, v89, s0
	global_store_short v[6:7], v0, off offset:64
	v_or_b32_e32 v6, 40, v4
	v_ashrrev_i32_e32 v7, 31, v6
	v_lshlrev_b64 v[6:7], 11, v[6:7]
	v_cvt_pk_bf16_f32 v0, v90, s0
	v_lshl_add_u64 v[6:7], v[2:3], 0, v[6:7]
	global_store_short v[6:7], v0, off
	v_cvt_pk_bf16_f32 v0, v84, s0
	global_store_short v[6:7], v0, off offset:64
	v_or_b32_e32 v6, 41, v4
	v_ashrrev_i32_e32 v7, 31, v6
	v_lshlrev_b64 v[6:7], 11, v[6:7]
	v_cvt_pk_bf16_f32 v0, v91, s0
	v_lshl_add_u64 v[6:7], v[2:3], 0, v[6:7]
	global_store_short v[6:7], v0, off
	v_cvt_pk_bf16_f32 v0, v85, s0
	global_store_short v[6:7], v0, off offset:64
	v_or_b32_e32 v6, 42, v4
	v_ashrrev_i32_e32 v7, 31, v6
	v_lshlrev_b64 v[6:7], 11, v[6:7]
	v_cvt_pk_bf16_f32 v0, v86, s0
	v_lshl_add_u64 v[6:7], v[2:3], 0, v[6:7]
	global_store_short v[6:7], v0, off
	v_cvt_pk_bf16_f32 v0, v80, s0
	global_store_short v[6:7], v0, off offset:64
	v_or_b32_e32 v6, 43, v4
	v_ashrrev_i32_e32 v7, 31, v6
	v_lshlrev_b64 v[6:7], 11, v[6:7]
	v_cvt_pk_bf16_f32 v0, v87, s0
	v_lshl_add_u64 v[6:7], v[2:3], 0, v[6:7]
	global_store_short v[6:7], v0, off
	v_cvt_pk_bf16_f32 v0, v81, s0
	global_store_short v[6:7], v0, off offset:64
	v_or_b32_e32 v6, 48, v4
	v_ashrrev_i32_e32 v7, 31, v6
	v_lshlrev_b64 v[6:7], 11, v[6:7]
	v_cvt_pk_bf16_f32 v0, v82, s0
	v_lshl_add_u64 v[6:7], v[2:3], 0, v[6:7]
	global_store_short v[6:7], v0, off
	v_cvt_pk_bf16_f32 v0, v76, s0
	global_store_short v[6:7], v0, off offset:64
	v_or_b32_e32 v6, 49, v4
	v_ashrrev_i32_e32 v7, 31, v6
	v_lshlrev_b64 v[6:7], 11, v[6:7]
	v_cvt_pk_bf16_f32 v0, v83, s0
	v_lshl_add_u64 v[6:7], v[2:3], 0, v[6:7]
	global_store_short v[6:7], v0, off
	v_cvt_pk_bf16_f32 v0, v77, s0
	global_store_short v[6:7], v0, off offset:64
	v_or_b32_e32 v6, 50, v4
	v_ashrrev_i32_e32 v7, 31, v6
	v_lshlrev_b64 v[6:7], 11, v[6:7]
	v_cvt_pk_bf16_f32 v0, v78, s0
	v_lshl_add_u64 v[6:7], v[2:3], 0, v[6:7]
	global_store_short v[6:7], v0, off
	v_cvt_pk_bf16_f32 v0, v72, s0
	global_store_short v[6:7], v0, off offset:64
	v_or_b32_e32 v6, 51, v4
	v_ashrrev_i32_e32 v7, 31, v6
	v_lshlrev_b64 v[6:7], 11, v[6:7]
	v_cvt_pk_bf16_f32 v0, v79, s0
	v_lshl_add_u64 v[6:7], v[2:3], 0, v[6:7]
	global_store_short v[6:7], v0, off
	v_cvt_pk_bf16_f32 v0, v73, s0
	global_store_short v[6:7], v0, off offset:64
	v_or_b32_e32 v6, 56, v4
	v_ashrrev_i32_e32 v7, 31, v6
	v_lshlrev_b64 v[6:7], 11, v[6:7]
	v_cvt_pk_bf16_f32 v0, v74, s0
	v_lshl_add_u64 v[6:7], v[2:3], 0, v[6:7]
	global_store_short v[6:7], v0, off
	v_cvt_pk_bf16_f32 v0, v70, s0
	global_store_short v[6:7], v0, off offset:64
	v_or_b32_e32 v6, 57, v4
	v_ashrrev_i32_e32 v7, 31, v6
	v_lshlrev_b64 v[6:7], 11, v[6:7]
	v_cvt_pk_bf16_f32 v0, v75, s0
	v_lshl_add_u64 v[6:7], v[2:3], 0, v[6:7]
	global_store_short v[6:7], v0, off
	v_cvt_pk_bf16_f32 v0, v71, s0
	global_store_short v[6:7], v0, off offset:64
	v_or_b32_e32 v6, 58, v4
	v_ashrrev_i32_e32 v7, 31, v6
	v_lshlrev_b64 v[6:7], 11, v[6:7]
	v_or_b32_e32 v4, 59, v4
	v_cvt_pk_bf16_f32 v0, v68, s0
	v_lshl_add_u64 v[6:7], v[2:3], 0, v[6:7]
	v_ashrrev_i32_e32 v5, 31, v4
	global_store_short v[6:7], v0, off
	v_cvt_pk_bf16_f32 v0, v66, s0
	v_lshlrev_b64 v[4:5], 11, v[4:5]
	global_store_short v[6:7], v0, off offset:64
	v_cvt_pk_bf16_f32 v0, v69, s0
	v_lshl_add_u64 v[2:3], v[2:3], 0, v[4:5]
	global_store_short v[2:3], v0, off
	v_cvt_pk_bf16_f32 v0, v67, s0
	global_store_short v[2:3], v0, off offset:64
	v_mov_b32_e32 v0, v133
	s_waitcnt vmcnt(63) expcnt(7) lgkmcnt(15)
	s_barrier
	s_nop 0
	v_cmp_eq_u32_e32 vcc, 0, v0
	s_and_saveexec_b64 s[4:5], vcc
	s_cbranch_execz .LBB0_103
	s_mov_b64 s[8:9], 0
	s_branch .LBB0_114

.LBB0_142:
	v_or_b32_e32 v106, s4, v104
	v_cndmask_b32_e64 v0, 0, 1, s[60:61]
	v_lshlrev_b32_e32 v107, 9, v106
	v_cmp_ne_u32_e64 s[38:39], 1, v0
	v_or_b32_e32 v0, v107, v100
	v_lshl_add_u64 v[68:69], v[0:1], 1, s[30:31]
	global_load_ushort v220, v[68:69], off
	v_mad_u64_u32 v[98:99], s[4:5], v106, s27, v[66:67]
	v_or_b32_e32 v70, 1, v106
	v_lshlrev_b32_e32 v108, 9, v70
	v_mad_u64_u32 v[96:97], s[4:5], v70, s27, v[66:67]
	v_or_b32_e32 v70, 2, v106
	v_lshlrev_b32_e32 v109, 9, v70
	v_mad_u64_u32 v[94:95], s[4:5], v70, s27, v[66:67]
	v_or_b32_e32 v70, 3, v106
	v_lshlrev_b32_e32 v110, 9, v70
	v_mad_u64_u32 v[92:93], s[4:5], v70, s27, v[66:67]
	v_or_b32_e32 v70, 8, v106
	v_lshlrev_b32_e32 v111, 9, v70
	v_mad_u64_u32 v[90:91], s[4:5], v70, s27, v[66:67]
	v_or_b32_e32 v70, 9, v106
	v_lshlrev_b32_e32 v112, 9, v70
	v_mad_u64_u32 v[88:89], s[4:5], v70, s27, v[66:67]
	v_or_b32_e32 v70, 10, v106
	v_lshlrev_b32_e32 v113, 9, v70
	v_mad_u64_u32 v[86:87], s[4:5], v70, s27, v[66:67]
	v_or_b32_e32 v70, 11, v106
	v_lshlrev_b32_e32 v114, 9, v70
	v_mad_u64_u32 v[84:85], s[4:5], v70, s27, v[66:67]
	v_or_b32_e32 v70, 16, v106
	v_lshlrev_b32_e32 v115, 9, v70
	v_mad_u64_u32 v[82:83], s[4:5], v70, s27, v[66:67]
	v_or_b32_e32 v70, 17, v106
	v_lshlrev_b32_e32 v116, 9, v70
	v_mad_u64_u32 v[80:81], s[4:5], v70, s27, v[66:67]
	v_or_b32_e32 v70, 18, v106
	v_lshlrev_b32_e32 v222, 9, v70
	v_mad_u64_u32 v[78:79], s[4:5], v70, s27, v[66:67]
	v_or_b32_e32 v70, 19, v106
	v_lshlrev_b32_e32 v223, 9, v70
	v_mad_u64_u32 v[76:77], s[4:5], v70, s27, v[66:67]
	v_or_b32_e32 v70, 24, v106
	v_lshlrev_b32_e32 v224, 9, v70
	v_mad_u64_u32 v[74:75], s[4:5], v70, s27, v[66:67]
	v_or_b32_e32 v70, 25, v106
	v_lshlrev_b32_e32 v225, 9, v70
	v_mad_u64_u32 v[72:73], s[4:5], v70, s27, v[66:67]
	v_or_b32_e32 v70, 26, v106
	v_lshlrev_b32_e32 v226, 9, v70
	v_mad_u64_u32 v[70:71], s[4:5], v70, s27, v[66:67]
	v_or_b32_e32 v106, 27, v106
	v_lshlrev_b32_e32 v227, 9, v106
	global_load_ushort v221, v[98:99], off offset:1024
	v_or_b32_e32 v0, v108, v100
	v_lshl_add_u64 v[68:69], v[0:1], 1, s[30:31]
	global_load_ushort v218, v[68:69], off
	global_load_ushort v219, v[96:97], off offset:1024
	v_or_b32_e32 v0, v109, v100
	v_lshl_add_u64 v[68:69], v[0:1], 1, s[30:31]
	global_load_ushort v216, v[68:69], off
	global_load_ushort v217, v[94:95], off offset:1024
	v_or_b32_e32 v0, v110, v100
	v_lshl_add_u64 v[68:69], v[0:1], 1, s[30:31]
	global_load_ushort v214, v[68:69], off
	global_load_ushort v215, v[92:93], off offset:1024
	v_or_b32_e32 v0, v111, v100
	v_lshl_add_u64 v[68:69], v[0:1], 1, s[30:31]
	global_load_ushort v183, v[68:69], off
	global_load_ushort v213, v[90:91], off offset:1024
	v_or_b32_e32 v0, v112, v100
	v_lshl_add_u64 v[68:69], v[0:1], 1, s[30:31]
	global_load_ushort v181, v[68:69], off
	global_load_ushort v182, v[88:89], off offset:1024
	v_or_b32_e32 v0, v113, v100
	v_lshl_add_u64 v[68:69], v[0:1], 1, s[30:31]
	global_load_ushort v179, v[68:69], off
	global_load_ushort v180, v[86:87], off offset:1024
	v_or_b32_e32 v0, v114, v100
	v_lshl_add_u64 v[68:69], v[0:1], 1, s[30:31]
	global_load_ushort v177, v[68:69], off
	global_load_ushort v178, v[84:85], off offset:1024
	v_or_b32_e32 v0, v115, v100
	v_lshl_add_u64 v[68:69], v[0:1], 1, s[30:31]
	global_load_ushort v175, v[68:69], off
	global_load_ushort v176, v[82:83], off offset:1024
	v_or_b32_e32 v0, v116, v100
	v_lshl_add_u64 v[68:69], v[0:1], 1, s[30:31]
	global_load_ushort v173, v[68:69], off
	global_load_ushort v174, v[80:81], off offset:1024
	v_or_b32_e32 v0, v222, v100
	v_lshl_add_u64 v[68:69], v[0:1], 1, s[30:31]
	global_load_ushort v171, v[68:69], off
	global_load_ushort v172, v[78:79], off offset:1024
	v_or_b32_e32 v0, v223, v100
	v_lshl_add_u64 v[68:69], v[0:1], 1, s[30:31]
	global_load_ushort v169, v[68:69], off
	global_load_ushort v170, v[76:77], off offset:1024
	v_or_b32_e32 v0, v224, v100
	v_lshl_add_u64 v[68:69], v[0:1], 1, s[30:31]
	global_load_ushort v167, v[68:69], off
	global_load_ushort v168, v[74:75], off offset:1024
	v_or_b32_e32 v0, v225, v100
	v_lshl_add_u64 v[68:69], v[0:1], 1, s[30:31]
	global_load_ushort v165, v[68:69], off
	global_load_ushort v166, v[72:73], off offset:1024
	s_waitcnt vmcnt(20)
	v_or_b32_e32 v0, v226, v100
	v_lshl_add_u64 v[68:69], v[0:1], 1, s[30:31]
	global_load_ushort v163, v[68:69], off
	global_load_ushort v164, v[70:71], off offset:1024
	v_or_b32_e32 v0, v227, v100
	v_lshl_add_u64 v[68:69], v[0:1], 1, s[30:31]
	global_load_ushort v161, v[68:69], off
	v_mad_u64_u32 v[68:69], s[4:5], v106, s27, v[66:67]
	global_load_ushort v162, v[68:69], off offset:1024
	v_or_b32_e32 v0, v107, v103
	v_lshl_add_u64 v[106:107], v[0:1], 1, s[30:31]
	global_load_ushort v159, v[106:107], off
	global_load_ushort v160, v[98:99], off offset:1088
	v_or_b32_e32 v0, v108, v103
	v_lshl_add_u64 v[106:107], v[0:1], 1, s[30:31]
	global_load_ushort v156, v[106:107], off
	global_load_ushort v158, v[96:97], off offset:1088
	v_or_b32_e32 v0, v109, v103
	v_lshl_add_u64 v[106:107], v[0:1], 1, s[30:31]
	global_load_ushort v135, v[106:107], off
	global_load_ushort v152, v[94:95], off offset:1088
	v_or_b32_e32 v0, v110, v103
	v_lshl_add_u64 v[106:107], v[0:1], 1, s[30:31]
	global_load_ushort v129, v[106:107], off
	global_load_ushort v131, v[92:93], off offset:1088
	v_or_b32_e32 v0, v111, v103
	v_lshl_add_u64 v[106:107], v[0:1], 1, s[30:31]
	global_load_ushort v127, v[106:107], off
	global_load_ushort v128, v[90:91], off offset:1088
	v_or_b32_e32 v0, v112, v103
	v_lshl_add_u64 v[106:107], v[0:1], 1, s[30:31]
	global_load_ushort v125, v[106:107], off
	global_load_ushort v126, v[88:89], off offset:1088
	v_or_b32_e32 v0, v113, v103
	v_lshl_add_u64 v[106:107], v[0:1], 1, s[30:31]
	global_load_ushort v123, v[106:107], off
	global_load_ushort v124, v[86:87], off offset:1088
	v_or_b32_e32 v0, v114, v103
	v_lshl_add_u64 v[106:107], v[0:1], 1, s[30:31]
	global_load_ushort v121, v[106:107], off
	global_load_ushort v122, v[84:85], off offset:1088
	v_or_b32_e32 v0, v115, v103
	v_lshl_add_u64 v[106:107], v[0:1], 1, s[30:31]
	global_load_ushort v119, v[106:107], off
	global_load_ushort v120, v[82:83], off offset:1088
	v_or_b32_e32 v0, v116, v103
	v_lshl_add_u64 v[106:107], v[0:1], 1, s[30:31]
	global_load_ushort v117, v[106:107], off
	global_load_ushort v118, v[80:81], off offset:1088
	v_or_b32_e32 v0, v222, v103
	v_lshl_add_u64 v[106:107], v[0:1], 1, s[30:31]
	global_load_ushort v115, v[106:107], off
	global_load_ushort v116, v[78:79], off offset:1088
	v_or_b32_e32 v0, v223, v103
	v_lshl_add_u64 v[106:107], v[0:1], 1, s[30:31]
	global_load_ushort v113, v[106:107], off
	global_load_ushort v114, v[76:77], off offset:1088
	s_waitcnt vmcnt(20)
	v_or_b32_e32 v0, v224, v103
	v_lshl_add_u64 v[106:107], v[0:1], 1, s[30:31]
	global_load_ushort v111, v[106:107], off
	global_load_ushort v112, v[74:75], off offset:1088
	v_or_b32_e32 v0, v225, v103
	v_lshl_add_u64 v[106:107], v[0:1], 1, s[30:31]
	global_load_ushort v109, v[106:107], off
	global_load_ushort v110, v[72:73], off offset:1088
	v_or_b32_e32 v0, v226, v103
	v_lshl_add_u64 v[106:107], v[0:1], 1, s[30:31]
	global_load_ushort v107, v[106:107], off
	s_waitcnt vmcnt(0)
	v_lshlrev_b32_e32 v220, 16, v220
	v_lshlrev_b32_e32 v221, 16, v221
	v_lshlrev_b32_e32 v218, 16, v218
	v_lshlrev_b32_e32 v219, 16, v219
	v_lshlrev_b32_e32 v216, 16, v216
	v_lshlrev_b32_e32 v217, 16, v217
	v_lshlrev_b32_e32 v214, 16, v214
	v_lshlrev_b32_e32 v215, 16, v215
	v_lshlrev_b32_e32 v183, 16, v183
	v_lshlrev_b32_e32 v213, 16, v213
	v_lshlrev_b32_e32 v181, 16, v181
	v_lshlrev_b32_e32 v182, 16, v182
	v_lshlrev_b32_e32 v179, 16, v179
	v_lshlrev_b32_e32 v180, 16, v180
	v_lshlrev_b32_e32 v177, 16, v177
	v_lshlrev_b32_e32 v178, 16, v178
	v_lshlrev_b32_e32 v175, 16, v175
	v_lshlrev_b32_e32 v176, 16, v176
	v_lshlrev_b32_e32 v173, 16, v173
	v_lshlrev_b32_e32 v174, 16, v174
	v_lshlrev_b32_e32 v171, 16, v171
	v_lshlrev_b32_e32 v172, 16, v172
	v_lshlrev_b32_e32 v169, 16, v169
	v_lshlrev_b32_e32 v170, 16, v170
	v_lshlrev_b32_e32 v167, 16, v167
	v_lshlrev_b32_e32 v168, 16, v168
	v_lshlrev_b32_e32 v165, 16, v165
	v_lshlrev_b32_e32 v166, 16, v166
	v_lshlrev_b32_e32 v163, 16, v163
	v_lshlrev_b32_e32 v164, 16, v164
	v_lshlrev_b32_e32 v161, 16, v161
	v_lshlrev_b32_e32 v162, 16, v162
	v_lshlrev_b32_e32 v159, 16, v159
	v_lshlrev_b32_e32 v160, 16, v160
	v_lshlrev_b32_e32 v156, 16, v156
	v_lshlrev_b32_e32 v158, 16, v158
	v_lshlrev_b32_e32 v135, 16, v135
	v_lshlrev_b32_e32 v152, 16, v152
	v_lshlrev_b32_e32 v129, 16, v129
	v_lshlrev_b32_e32 v131, 16, v131
	v_lshlrev_b32_e32 v127, 16, v127
	v_lshlrev_b32_e32 v128, 16, v128
	v_lshlrev_b32_e32 v125, 16, v125
	v_lshlrev_b32_e32 v126, 16, v126
	v_lshlrev_b32_e32 v123, 16, v123
	v_lshlrev_b32_e32 v124, 16, v124
	v_lshlrev_b32_e32 v121, 16, v121
	v_lshlrev_b32_e32 v122, 16, v122
	v_lshlrev_b32_e32 v119, 16, v119
	v_lshlrev_b32_e32 v120, 16, v120
	v_lshlrev_b32_e32 v117, 16, v117
	v_lshlrev_b32_e32 v118, 16, v118
	v_lshlrev_b32_e32 v115, 16, v115
	v_lshlrev_b32_e32 v116, 16, v116
	v_lshlrev_b32_e32 v113, 16, v113
	v_lshlrev_b32_e32 v114, 16, v114
	v_lshlrev_b32_e32 v111, 16, v111
	v_lshlrev_b32_e32 v112, 16, v112
	v_lshlrev_b32_e32 v109, 16, v109
	v_lshlrev_b32_e32 v110, 16, v110
	v_lshlrev_b32_e32 v107, 16, v107
	global_load_ushort v0, v[70:71], off offset:1088
	global_load_ushort v106, v[68:69], off offset:1088
	s_waitcnt vmcnt(1)
	v_lshlrev_b32_e32 v108, 16, v0
	v_or_b32_e32 v0, v227, v103
	v_lshl_add_u64 v[222:223], v[0:1], 1, s[30:31]
	global_load_ushort v0, v[222:223], off
	v_cndmask_b32_e64 v222, v18, v2, s[60:61]
	v_add_f32_e32 v222, v101, v222
	v_mul_f32_e32 v222, 0xbfb8aa3b, v222
	v_exp_f32_e32 v222, v222
	s_waitcnt vmcnt(1)
	v_lshlrev_b32_e32 v106, 16, v106
	v_add_f32_e32 v222, 1.0, v222
	v_div_scale_f32 v223, s[4:5], v222, v222, 1.0
	v_rcp_f32_e32 v224, v223
	s_waitcnt vmcnt(0)
	v_lshlrev_b32_e32 v0, 16, v0
	v_fma_f32 v225, -v223, v224, 1.0
	v_fmac_f32_e32 v224, v225, v224
	v_div_scale_f32 v225, vcc, 1.0, v222, 1.0
	v_mul_f32_e32 v226, v225, v224
	v_fma_f32 v227, -v223, v226, v225
	v_fmac_f32_e32 v226, v227, v224
	v_fma_f32 v223, -v223, v226, v225
	v_div_fmas_f32 v223, v223, v224, v226
	v_div_fixup_f32 v222, v223, v222, 1.0
	v_mul_f32_e32 v220, v222, v220
	v_mul_f32_e32 v220, v220, v221
	v_cvt_pk_bf16_f32 v220, v220, s0
	global_store_short v[98:99], v220, off offset:1024
	v_cndmask_b32_e64 v220, v19, v3, s[60:61]
	v_add_f32_e32 v220, v101, v220
	v_mul_f32_e32 v220, 0xbfb8aa3b, v220
	v_exp_f32_e32 v220, v220
	s_nop 0
	v_add_f32_e32 v220, 1.0, v220
	v_div_scale_f32 v221, s[4:5], v220, v220, 1.0
	v_rcp_f32_e32 v222, v221
	s_nop 0
	v_fma_f32 v223, -v221, v222, 1.0
	v_fmac_f32_e32 v222, v223, v222
	v_div_scale_f32 v223, vcc, 1.0, v220, 1.0
	v_mul_f32_e32 v224, v223, v222
	v_fma_f32 v225, -v221, v224, v223
	v_fmac_f32_e32 v224, v225, v222
	v_fma_f32 v221, -v221, v224, v223
	v_div_fmas_f32 v221, v221, v222, v224
	v_div_fixup_f32 v220, v221, v220, 1.0
	v_mul_f32_e32 v218, v220, v218
	v_mul_f32_e32 v218, v218, v219
	v_cvt_pk_bf16_f32 v218, v218, s0
	global_store_short v[96:97], v218, off offset:1024
	v_cndmask_b32_e64 v218, v20, v4, s[60:61]
	v_add_f32_e32 v218, v101, v218
	v_mul_f32_e32 v218, 0xbfb8aa3b, v218
	v_exp_f32_e32 v218, v218
	s_nop 0
	v_add_f32_e32 v218, 1.0, v218
	v_div_scale_f32 v219, s[4:5], v218, v218, 1.0
	v_rcp_f32_e32 v220, v219
	s_nop 0
	v_fma_f32 v221, -v219, v220, 1.0
	v_fmac_f32_e32 v220, v221, v220
	v_div_scale_f32 v221, vcc, 1.0, v218, 1.0
	v_mul_f32_e32 v222, v221, v220
	v_fma_f32 v223, -v219, v222, v221
	v_fmac_f32_e32 v222, v223, v220
	v_fma_f32 v219, -v219, v222, v221
	v_div_fmas_f32 v219, v219, v220, v222
	v_div_fixup_f32 v218, v219, v218, 1.0
	v_mul_f32_e32 v216, v218, v216
	v_mul_f32_e32 v216, v216, v217
	v_cvt_pk_bf16_f32 v216, v216, s0
	global_store_short v[94:95], v216, off offset:1024
	v_cndmask_b32_e64 v216, v21, v5, s[60:61]
	v_add_f32_e32 v216, v101, v216
	v_mul_f32_e32 v216, 0xbfb8aa3b, v216
	v_exp_f32_e32 v216, v216
	s_nop 0
	v_add_f32_e32 v216, 1.0, v216
	v_div_scale_f32 v217, s[4:5], v216, v216, 1.0
	v_rcp_f32_e32 v218, v217
	s_nop 0
	v_fma_f32 v219, -v217, v218, 1.0
	v_fmac_f32_e32 v218, v219, v218
	v_div_scale_f32 v219, vcc, 1.0, v216, 1.0
	v_mul_f32_e32 v220, v219, v218
	v_fma_f32 v221, -v217, v220, v219
	v_fmac_f32_e32 v220, v221, v218
	v_fma_f32 v217, -v217, v220, v219
	v_div_fmas_f32 v217, v217, v218, v220
	v_div_fixup_f32 v216, v217, v216, 1.0
	v_mul_f32_e32 v214, v216, v214
	v_mul_f32_e32 v214, v214, v215
	v_cvt_pk_bf16_f32 v214, v214, s0
	global_store_short v[92:93], v214, off offset:1024
	v_cndmask_b32_e64 v214, v22, v6, s[60:61]
	v_add_f32_e32 v214, v101, v214
	v_mul_f32_e32 v214, 0xbfb8aa3b, v214
	v_exp_f32_e32 v214, v214
	s_nop 0
	v_add_f32_e32 v214, 1.0, v214
	v_div_scale_f32 v215, s[4:5], v214, v214, 1.0
	v_rcp_f32_e32 v216, v215
	s_nop 0
	v_fma_f32 v217, -v215, v216, 1.0
	v_fmac_f32_e32 v216, v217, v216
	v_div_scale_f32 v217, vcc, 1.0, v214, 1.0
	v_mul_f32_e32 v218, v217, v216
	v_fma_f32 v219, -v215, v218, v217
	v_fmac_f32_e32 v218, v219, v216
	v_fma_f32 v215, -v215, v218, v217
	v_div_fmas_f32 v215, v215, v216, v218
	v_div_fixup_f32 v214, v215, v214, 1.0
	v_mul_f32_e32 v183, v214, v183
	v_mul_f32_e32 v183, v183, v213
	v_cvt_pk_bf16_f32 v183, v183, s0
	global_store_short v[90:91], v183, off offset:1024
	v_cndmask_b32_e64 v183, v23, v7, s[60:61]
	v_add_f32_e32 v183, v101, v183
	v_mul_f32_e32 v183, 0xbfb8aa3b, v183
	v_exp_f32_e32 v183, v183
	s_nop 0
	v_add_f32_e32 v183, 1.0, v183
	v_div_scale_f32 v213, s[4:5], v183, v183, 1.0
	v_rcp_f32_e32 v214, v213
	s_nop 0
	v_fma_f32 v215, -v213, v214, 1.0
	v_fmac_f32_e32 v214, v215, v214
	v_div_scale_f32 v215, vcc, 1.0, v183, 1.0
	v_mul_f32_e32 v216, v215, v214
	v_fma_f32 v217, -v213, v216, v215
	v_fmac_f32_e32 v216, v217, v214
	v_fma_f32 v213, -v213, v216, v215
	v_div_fmas_f32 v213, v213, v214, v216
	v_div_fixup_f32 v183, v213, v183, 1.0
	v_mul_f32_e32 v181, v183, v181
	v_mul_f32_e32 v181, v181, v182
	v_cvt_pk_bf16_f32 v181, v181, s0
	global_store_short v[88:89], v181, off offset:1024
	v_cndmask_b32_e64 v181, v24, v8, s[60:61]
	v_add_f32_e32 v181, v101, v181
	v_mul_f32_e32 v181, 0xbfb8aa3b, v181
	v_exp_f32_e32 v181, v181
	s_nop 0
	v_add_f32_e32 v181, 1.0, v181
	v_div_scale_f32 v182, s[4:5], v181, v181, 1.0
	v_rcp_f32_e32 v183, v182
	s_nop 0
	v_fma_f32 v213, -v182, v183, 1.0
	v_fmac_f32_e32 v183, v213, v183
	v_div_scale_f32 v213, vcc, 1.0, v181, 1.0
	v_mul_f32_e32 v214, v213, v183
	v_fma_f32 v215, -v182, v214, v213
	v_fmac_f32_e32 v214, v215, v183
	v_fma_f32 v182, -v182, v214, v213
	v_div_fmas_f32 v182, v182, v183, v214
	v_div_fixup_f32 v181, v182, v181, 1.0
	v_mul_f32_e32 v179, v181, v179
	v_mul_f32_e32 v179, v179, v180
	v_cvt_pk_bf16_f32 v179, v179, s0
	global_store_short v[86:87], v179, off offset:1024
	v_cndmask_b32_e64 v179, v25, v9, s[60:61]
	v_add_f32_e32 v179, v101, v179
	v_mul_f32_e32 v179, 0xbfb8aa3b, v179
	v_exp_f32_e32 v179, v179
	s_nop 0
	v_add_f32_e32 v179, 1.0, v179
	v_div_scale_f32 v180, s[4:5], v179, v179, 1.0
	v_rcp_f32_e32 v181, v180
	s_nop 0
	v_fma_f32 v182, -v180, v181, 1.0
	v_fmac_f32_e32 v181, v182, v181
	v_div_scale_f32 v182, vcc, 1.0, v179, 1.0
	v_mul_f32_e32 v183, v182, v181
	v_fma_f32 v213, -v180, v183, v182
	v_fmac_f32_e32 v183, v213, v181
	v_fma_f32 v180, -v180, v183, v182
	v_div_fmas_f32 v180, v180, v181, v183
	v_div_fixup_f32 v179, v180, v179, 1.0
	v_mul_f32_e32 v177, v179, v177
	v_mul_f32_e32 v177, v177, v178
	v_cvt_pk_bf16_f32 v177, v177, s0
	global_store_short v[84:85], v177, off offset:1024
	v_cndmask_b32_e64 v177, v26, v10, s[60:61]
	v_add_f32_e32 v177, v101, v177
	v_mul_f32_e32 v177, 0xbfb8aa3b, v177
	v_exp_f32_e32 v177, v177
	s_nop 0
	v_add_f32_e32 v177, 1.0, v177
	v_div_scale_f32 v178, s[4:5], v177, v177, 1.0
	v_rcp_f32_e32 v179, v178
	s_nop 0
	v_fma_f32 v180, -v178, v179, 1.0
	v_fmac_f32_e32 v179, v180, v179
	v_div_scale_f32 v180, vcc, 1.0, v177, 1.0
	v_mul_f32_e32 v181, v180, v179
	v_fma_f32 v182, -v178, v181, v180
	v_fmac_f32_e32 v181, v182, v179
	v_fma_f32 v178, -v178, v181, v180
	v_div_fmas_f32 v178, v178, v179, v181
	v_div_fixup_f32 v177, v178, v177, 1.0
	v_mul_f32_e32 v175, v177, v175
	v_mul_f32_e32 v175, v175, v176
	v_cvt_pk_bf16_f32 v175, v175, s0
	global_store_short v[82:83], v175, off offset:1024
	v_cndmask_b32_e64 v175, v27, v11, s[60:61]
	v_add_f32_e32 v175, v101, v175
	v_mul_f32_e32 v175, 0xbfb8aa3b, v175
	v_exp_f32_e32 v175, v175
	s_nop 0
	v_add_f32_e32 v175, 1.0, v175
	v_div_scale_f32 v176, s[4:5], v175, v175, 1.0
	v_rcp_f32_e32 v177, v176
	s_nop 0
	v_fma_f32 v178, -v176, v177, 1.0
	v_fmac_f32_e32 v177, v178, v177
	v_div_scale_f32 v178, vcc, 1.0, v175, 1.0
	v_mul_f32_e32 v179, v178, v177
	v_fma_f32 v180, -v176, v179, v178
	v_fmac_f32_e32 v179, v180, v177
	v_fma_f32 v176, -v176, v179, v178
	v_div_fmas_f32 v176, v176, v177, v179
	v_div_fixup_f32 v175, v176, v175, 1.0
	v_mul_f32_e32 v173, v175, v173
	v_mul_f32_e32 v173, v173, v174
	v_cvt_pk_bf16_f32 v173, v173, s0
	global_store_short v[80:81], v173, off offset:1024
	v_cndmask_b32_e64 v173, v28, v12, s[60:61]
	v_add_f32_e32 v173, v101, v173
	v_mul_f32_e32 v173, 0xbfb8aa3b, v173
	v_exp_f32_e32 v173, v173
	s_nop 0
	v_add_f32_e32 v173, 1.0, v173
	v_div_scale_f32 v174, s[4:5], v173, v173, 1.0
	v_rcp_f32_e32 v175, v174
	s_nop 0
	v_fma_f32 v176, -v174, v175, 1.0
	v_fmac_f32_e32 v175, v176, v175
	v_div_scale_f32 v176, vcc, 1.0, v173, 1.0
	v_mul_f32_e32 v177, v176, v175
	v_fma_f32 v178, -v174, v177, v176
	v_fmac_f32_e32 v177, v178, v175
	v_fma_f32 v174, -v174, v177, v176
	v_div_fmas_f32 v174, v174, v175, v177
	v_div_fixup_f32 v173, v174, v173, 1.0
	v_mul_f32_e32 v171, v173, v171
	v_mul_f32_e32 v171, v171, v172
	v_cvt_pk_bf16_f32 v171, v171, s0
	global_store_short v[78:79], v171, off offset:1024
	v_cndmask_b32_e64 v171, v29, v13, s[60:61]
	v_add_f32_e32 v171, v101, v171
	v_mul_f32_e32 v171, 0xbfb8aa3b, v171
	v_exp_f32_e32 v171, v171
	s_nop 0
	v_add_f32_e32 v171, 1.0, v171
	v_div_scale_f32 v172, s[4:5], v171, v171, 1.0
	v_rcp_f32_e32 v173, v172
	s_nop 0
	v_fma_f32 v174, -v172, v173, 1.0
	v_fmac_f32_e32 v173, v174, v173
	v_div_scale_f32 v174, vcc, 1.0, v171, 1.0
	v_mul_f32_e32 v175, v174, v173
	v_fma_f32 v176, -v172, v175, v174
	v_fmac_f32_e32 v175, v176, v173
	v_fma_f32 v172, -v172, v175, v174
	v_div_fmas_f32 v172, v172, v173, v175
	v_div_fixup_f32 v171, v172, v171, 1.0
	v_mul_f32_e32 v169, v171, v169
	v_mul_f32_e32 v169, v169, v170
	v_cvt_pk_bf16_f32 v169, v169, s0
	global_store_short v[76:77], v169, off offset:1024
	v_cndmask_b32_e64 v169, v30, v14, s[60:61]
	v_add_f32_e32 v169, v101, v169
	v_mul_f32_e32 v169, 0xbfb8aa3b, v169
	v_exp_f32_e32 v169, v169
	s_nop 0
	v_add_f32_e32 v169, 1.0, v169
	v_div_scale_f32 v170, s[4:5], v169, v169, 1.0
	v_rcp_f32_e32 v171, v170
	s_nop 0
	v_fma_f32 v172, -v170, v171, 1.0
	v_fmac_f32_e32 v171, v172, v171
	v_div_scale_f32 v172, vcc, 1.0, v169, 1.0
	v_mul_f32_e32 v173, v172, v171
	v_fma_f32 v174, -v170, v173, v172
	v_fmac_f32_e32 v173, v174, v171
	v_fma_f32 v170, -v170, v173, v172
	v_div_fmas_f32 v170, v170, v171, v173
	v_div_fixup_f32 v169, v170, v169, 1.0
	v_mul_f32_e32 v167, v169, v167
	v_mul_f32_e32 v167, v167, v168
	v_cvt_pk_bf16_f32 v167, v167, s0
	global_store_short v[74:75], v167, off offset:1024
	v_cndmask_b32_e64 v167, v31, v15, s[60:61]
	v_add_f32_e32 v167, v101, v167
	v_mul_f32_e32 v167, 0xbfb8aa3b, v167
	v_exp_f32_e32 v167, v167
	s_nop 0
	v_add_f32_e32 v167, 1.0, v167
	v_div_scale_f32 v168, s[4:5], v167, v167, 1.0
	v_rcp_f32_e32 v169, v168
	s_nop 0
	v_fma_f32 v170, -v168, v169, 1.0
	v_fmac_f32_e32 v169, v170, v169
	v_div_scale_f32 v170, vcc, 1.0, v167, 1.0
	v_mul_f32_e32 v171, v170, v169
	v_fma_f32 v172, -v168, v171, v170
	v_fmac_f32_e32 v171, v172, v169
	v_fma_f32 v168, -v168, v171, v170
	v_div_fmas_f32 v168, v168, v169, v171
	v_div_fixup_f32 v167, v168, v167, 1.0
	v_mul_f32_e32 v165, v167, v165
	v_mul_f32_e32 v165, v165, v166
	v_cvt_pk_bf16_f32 v165, v165, s0
	global_store_short v[72:73], v165, off offset:1024
	v_cndmask_b32_e64 v165, v32, v16, s[60:61]
	v_add_f32_e32 v165, v101, v165
	v_mul_f32_e32 v165, 0xbfb8aa3b, v165
	v_exp_f32_e32 v165, v165
	s_nop 0
	v_add_f32_e32 v165, 1.0, v165
	v_div_scale_f32 v166, s[4:5], v165, v165, 1.0
	v_rcp_f32_e32 v167, v166
	s_nop 0
	v_fma_f32 v168, -v166, v167, 1.0
	v_fmac_f32_e32 v167, v168, v167
	v_div_scale_f32 v168, vcc, 1.0, v165, 1.0
	v_mul_f32_e32 v169, v168, v167
	v_fma_f32 v170, -v166, v169, v168
	v_fmac_f32_e32 v169, v170, v167
	v_fma_f32 v166, -v166, v169, v168
	v_div_fmas_f32 v166, v166, v167, v169
	v_div_fixup_f32 v165, v166, v165, 1.0
	v_mul_f32_e32 v163, v165, v163
	v_mul_f32_e32 v163, v163, v164
	v_cvt_pk_bf16_f32 v163, v163, s0
	global_store_short v[70:71], v163, off offset:1024
	v_cndmask_b32_e64 v163, v33, v17, s[60:61]
	v_add_f32_e32 v163, v101, v163
	v_mul_f32_e32 v163, 0xbfb8aa3b, v163
	v_exp_f32_e32 v163, v163
	s_nop 0
	v_add_f32_e32 v163, 1.0, v163
	v_div_scale_f32 v164, s[4:5], v163, v163, 1.0
	v_rcp_f32_e32 v165, v164
	s_nop 0
	v_fma_f32 v166, -v164, v165, 1.0
	v_fmac_f32_e32 v165, v166, v165
	v_div_scale_f32 v166, vcc, 1.0, v163, 1.0
	v_mul_f32_e32 v167, v166, v165
	v_fma_f32 v168, -v164, v167, v166
	v_fmac_f32_e32 v167, v168, v165
	v_fma_f32 v164, -v164, v167, v166
	v_div_fmas_f32 v164, v164, v165, v167
	v_div_fixup_f32 v163, v164, v163, 1.0
	v_mul_f32_e32 v161, v163, v161
	v_mul_f32_e32 v161, v161, v162
	v_cvt_pk_bf16_f32 v161, v161, s0
	global_store_short v[68:69], v161, off offset:1024
	v_cndmask_b32_e64 v161, v50, v34, s[60:61]
	v_add_f32_e32 v161, v102, v161
	v_mul_f32_e32 v161, 0xbfb8aa3b, v161
	v_exp_f32_e32 v161, v161
	s_nop 0
	v_add_f32_e32 v161, 1.0, v161
	v_div_scale_f32 v162, s[4:5], v161, v161, 1.0
	v_rcp_f32_e32 v163, v162
	s_nop 0
	v_fma_f32 v164, -v162, v163, 1.0
	v_fmac_f32_e32 v163, v164, v163
	v_div_scale_f32 v164, vcc, 1.0, v161, 1.0
	v_mul_f32_e32 v165, v164, v163
	v_fma_f32 v166, -v162, v165, v164
	v_fmac_f32_e32 v165, v166, v163
	v_fma_f32 v162, -v162, v165, v164
	v_div_fmas_f32 v162, v162, v163, v165
	v_div_fixup_f32 v161, v162, v161, 1.0
	v_mul_f32_e32 v159, v161, v159
	v_mul_f32_e32 v159, v159, v160
	v_cvt_pk_bf16_f32 v159, v159, s0
	global_store_short v[98:99], v159, off offset:1088
	v_cndmask_b32_e64 v98, v51, v35, s[60:61]
	v_add_f32_e32 v98, v102, v98
	v_mul_f32_e32 v98, 0xbfb8aa3b, v98
	v_exp_f32_e32 v98, v98
	s_nop 0
	v_add_f32_e32 v98, 1.0, v98
	v_div_scale_f32 v99, s[4:5], v98, v98, 1.0
	v_rcp_f32_e32 v159, v99
	s_nop 0
	v_fma_f32 v160, -v99, v159, 1.0
	v_fmac_f32_e32 v159, v160, v159
	v_div_scale_f32 v160, vcc, 1.0, v98, 1.0
	v_mul_f32_e32 v161, v160, v159
	v_fma_f32 v162, -v99, v161, v160
	v_fmac_f32_e32 v161, v162, v159
	v_fma_f32 v99, -v99, v161, v160
	v_div_fmas_f32 v99, v99, v159, v161
	v_div_fixup_f32 v98, v99, v98, 1.0
	v_mul_f32_e32 v98, v98, v156
	v_mul_f32_e32 v98, v98, v158
	v_cvt_pk_bf16_f32 v98, v98, s0
	global_store_short v[96:97], v98, off offset:1088
	v_cndmask_b32_e64 v96, v52, v36, s[60:61]
	v_add_f32_e32 v96, v102, v96
	v_mul_f32_e32 v96, 0xbfb8aa3b, v96
	v_exp_f32_e32 v96, v96
	s_nop 0
	v_add_f32_e32 v96, 1.0, v96
	v_div_scale_f32 v97, s[4:5], v96, v96, 1.0
	v_rcp_f32_e32 v98, v97
	s_nop 0
	v_fma_f32 v99, -v97, v98, 1.0
	v_fmac_f32_e32 v98, v99, v98
	v_div_scale_f32 v99, vcc, 1.0, v96, 1.0
	v_mul_f32_e32 v156, v99, v98
	v_fma_f32 v158, -v97, v156, v99
	v_fmac_f32_e32 v156, v158, v98
	v_fma_f32 v97, -v97, v156, v99
	v_div_fmas_f32 v97, v97, v98, v156
	v_div_fixup_f32 v96, v97, v96, 1.0
	v_mul_f32_e32 v96, v96, v135
	v_mul_f32_e32 v96, v96, v152
	v_cvt_pk_bf16_f32 v96, v96, s0
	global_store_short v[94:95], v96, off offset:1088
	v_cndmask_b32_e64 v94, v53, v37, s[60:61]
	v_add_f32_e32 v94, v102, v94
	v_mul_f32_e32 v94, 0xbfb8aa3b, v94
	v_exp_f32_e32 v94, v94
	s_nop 0
	v_add_f32_e32 v94, 1.0, v94
	v_div_scale_f32 v95, s[4:5], v94, v94, 1.0
	v_rcp_f32_e32 v96, v95
	s_nop 0
	v_fma_f32 v97, -v95, v96, 1.0
	v_fmac_f32_e32 v96, v97, v96
	v_div_scale_f32 v97, vcc, 1.0, v94, 1.0
	v_mul_f32_e32 v98, v97, v96
	v_fma_f32 v99, -v95, v98, v97
	v_fmac_f32_e32 v98, v99, v96
	v_fma_f32 v95, -v95, v98, v97
	v_div_fmas_f32 v95, v95, v96, v98
	v_div_fixup_f32 v94, v95, v94, 1.0
	v_mul_f32_e32 v94, v94, v129
	v_mul_f32_e32 v94, v94, v131
	v_cvt_pk_bf16_f32 v94, v94, s0
	global_store_short v[92:93], v94, off offset:1088
	v_cndmask_b32_e64 v92, v54, v38, s[60:61]
	v_add_f32_e32 v92, v102, v92
	v_mul_f32_e32 v92, 0xbfb8aa3b, v92
	v_exp_f32_e32 v92, v92
	s_nop 0
	v_add_f32_e32 v92, 1.0, v92
	v_div_scale_f32 v93, s[4:5], v92, v92, 1.0
	v_rcp_f32_e32 v94, v93
	s_nop 0
	v_fma_f32 v95, -v93, v94, 1.0
	v_fmac_f32_e32 v94, v95, v94
	v_div_scale_f32 v95, vcc, 1.0, v92, 1.0
	v_mul_f32_e32 v96, v95, v94
	v_fma_f32 v97, -v93, v96, v95
	v_fmac_f32_e32 v96, v97, v94
	v_fma_f32 v93, -v93, v96, v95
	v_div_fmas_f32 v93, v93, v94, v96
	v_div_fixup_f32 v92, v93, v92, 1.0
	v_mul_f32_e32 v92, v92, v127
	v_mul_f32_e32 v92, v92, v128
	v_cvt_pk_bf16_f32 v92, v92, s0
	global_store_short v[90:91], v92, off offset:1088
	v_cndmask_b32_e64 v90, v55, v39, s[60:61]
	v_add_f32_e32 v90, v102, v90
	v_mul_f32_e32 v90, 0xbfb8aa3b, v90
	v_exp_f32_e32 v90, v90
	s_nop 0
	v_add_f32_e32 v90, 1.0, v90
	v_div_scale_f32 v91, s[4:5], v90, v90, 1.0
	v_rcp_f32_e32 v92, v91
	s_nop 0
	v_fma_f32 v93, -v91, v92, 1.0
	v_fmac_f32_e32 v92, v93, v92
	v_div_scale_f32 v93, vcc, 1.0, v90, 1.0
	v_mul_f32_e32 v94, v93, v92
	v_fma_f32 v95, -v91, v94, v93
	v_fmac_f32_e32 v94, v95, v92
	v_fma_f32 v91, -v91, v94, v93
	v_div_fmas_f32 v91, v91, v92, v94
	v_div_fixup_f32 v90, v91, v90, 1.0
	v_mul_f32_e32 v90, v90, v125
	v_mul_f32_e32 v90, v90, v126
	v_cvt_pk_bf16_f32 v90, v90, s0
	global_store_short v[88:89], v90, off offset:1088
	v_cndmask_b32_e64 v88, v56, v40, s[60:61]
	v_add_f32_e32 v88, v102, v88
	v_mul_f32_e32 v88, 0xbfb8aa3b, v88
	v_exp_f32_e32 v88, v88
	s_nop 0
	v_add_f32_e32 v88, 1.0, v88
	v_div_scale_f32 v89, s[4:5], v88, v88, 1.0
	v_rcp_f32_e32 v90, v89
	s_nop 0
	v_fma_f32 v91, -v89, v90, 1.0
	v_fmac_f32_e32 v90, v91, v90
	v_div_scale_f32 v91, vcc, 1.0, v88, 1.0
	v_mul_f32_e32 v92, v91, v90
	v_fma_f32 v93, -v89, v92, v91
	v_fmac_f32_e32 v92, v93, v90
	v_fma_f32 v89, -v89, v92, v91
	v_div_fmas_f32 v89, v89, v90, v92
	v_div_fixup_f32 v88, v89, v88, 1.0
	v_mul_f32_e32 v88, v88, v123
	v_mul_f32_e32 v88, v88, v124
	v_cvt_pk_bf16_f32 v88, v88, s0
	global_store_short v[86:87], v88, off offset:1088
	v_cndmask_b32_e64 v86, v57, v41, s[60:61]
	v_add_f32_e32 v86, v102, v86
	v_mul_f32_e32 v86, 0xbfb8aa3b, v86
	v_exp_f32_e32 v86, v86
	s_nop 0
	v_add_f32_e32 v86, 1.0, v86
	v_div_scale_f32 v87, s[4:5], v86, v86, 1.0
	v_rcp_f32_e32 v88, v87
	s_nop 0
	v_fma_f32 v89, -v87, v88, 1.0
	v_fmac_f32_e32 v88, v89, v88
	v_div_scale_f32 v89, vcc, 1.0, v86, 1.0
	v_mul_f32_e32 v90, v89, v88
	v_fma_f32 v91, -v87, v90, v89
	v_fmac_f32_e32 v90, v91, v88
	v_fma_f32 v87, -v87, v90, v89
	v_div_fmas_f32 v87, v87, v88, v90
	v_div_fixup_f32 v86, v87, v86, 1.0
	v_mul_f32_e32 v86, v86, v121
	v_mul_f32_e32 v86, v86, v122
	v_cvt_pk_bf16_f32 v86, v86, s0
	global_store_short v[84:85], v86, off offset:1088
	v_cndmask_b32_e64 v84, v58, v42, s[60:61]
	v_add_f32_e32 v84, v102, v84
	v_mul_f32_e32 v84, 0xbfb8aa3b, v84
	v_exp_f32_e32 v84, v84
	s_nop 0
	v_add_f32_e32 v84, 1.0, v84
	v_div_scale_f32 v85, s[4:5], v84, v84, 1.0
	v_rcp_f32_e32 v86, v85
	s_nop 0
	v_fma_f32 v87, -v85, v86, 1.0
	v_fmac_f32_e32 v86, v87, v86
	v_div_scale_f32 v87, vcc, 1.0, v84, 1.0
	v_mul_f32_e32 v88, v87, v86
	v_fma_f32 v89, -v85, v88, v87
	v_fmac_f32_e32 v88, v89, v86
	v_fma_f32 v85, -v85, v88, v87
	v_div_fmas_f32 v85, v85, v86, v88
	v_div_fixup_f32 v84, v85, v84, 1.0
	v_mul_f32_e32 v84, v84, v119
	v_mul_f32_e32 v84, v84, v120
	v_cvt_pk_bf16_f32 v84, v84, s0
	global_store_short v[82:83], v84, off offset:1088
	v_cndmask_b32_e64 v82, v59, v43, s[60:61]
	v_add_f32_e32 v82, v102, v82
	v_mul_f32_e32 v82, 0xbfb8aa3b, v82
	v_exp_f32_e32 v82, v82
	s_nop 0
	v_add_f32_e32 v82, 1.0, v82
	v_div_scale_f32 v83, s[4:5], v82, v82, 1.0
	v_rcp_f32_e32 v84, v83
	s_nop 0
	v_fma_f32 v85, -v83, v84, 1.0
	v_fmac_f32_e32 v84, v85, v84
	v_div_scale_f32 v85, vcc, 1.0, v82, 1.0
	v_mul_f32_e32 v86, v85, v84
	v_fma_f32 v87, -v83, v86, v85
	v_fmac_f32_e32 v86, v87, v84
	v_fma_f32 v83, -v83, v86, v85
	v_div_fmas_f32 v83, v83, v84, v86
	v_div_fixup_f32 v82, v83, v82, 1.0
	v_mul_f32_e32 v82, v82, v117
	v_mul_f32_e32 v82, v82, v118
	v_cvt_pk_bf16_f32 v82, v82, s0
	global_store_short v[80:81], v82, off offset:1088
	v_cndmask_b32_e64 v80, v60, v44, s[60:61]
	v_add_f32_e32 v80, v102, v80
	v_mul_f32_e32 v80, 0xbfb8aa3b, v80
	v_exp_f32_e32 v80, v80
	s_nop 0
	v_add_f32_e32 v80, 1.0, v80
	v_div_scale_f32 v81, s[4:5], v80, v80, 1.0
	v_rcp_f32_e32 v82, v81
	s_nop 0
	v_fma_f32 v83, -v81, v82, 1.0
	v_fmac_f32_e32 v82, v83, v82
	v_div_scale_f32 v83, vcc, 1.0, v80, 1.0
	v_mul_f32_e32 v84, v83, v82
	v_fma_f32 v85, -v81, v84, v83
	v_fmac_f32_e32 v84, v85, v82
	v_fma_f32 v81, -v81, v84, v83
	v_div_fmas_f32 v81, v81, v82, v84
	v_div_fixup_f32 v80, v81, v80, 1.0
	v_mul_f32_e32 v80, v80, v115
	v_mul_f32_e32 v80, v80, v116
	v_cvt_pk_bf16_f32 v80, v80, s0
	global_store_short v[78:79], v80, off offset:1088
	v_cndmask_b32_e64 v78, v61, v45, s[60:61]
	v_add_f32_e32 v78, v102, v78
	v_mul_f32_e32 v78, 0xbfb8aa3b, v78
	v_exp_f32_e32 v78, v78
	s_nop 0
	v_add_f32_e32 v78, 1.0, v78
	v_div_scale_f32 v79, s[4:5], v78, v78, 1.0
	v_rcp_f32_e32 v80, v79
	s_nop 0
	v_fma_f32 v81, -v79, v80, 1.0
	v_fmac_f32_e32 v80, v81, v80
	v_div_scale_f32 v81, vcc, 1.0, v78, 1.0
	v_mul_f32_e32 v82, v81, v80
	v_fma_f32 v83, -v79, v82, v81
	v_fmac_f32_e32 v82, v83, v80
	v_fma_f32 v79, -v79, v82, v81
	v_div_fmas_f32 v79, v79, v80, v82
	v_div_fixup_f32 v78, v79, v78, 1.0
	v_mul_f32_e32 v78, v78, v113
	v_mul_f32_e32 v78, v78, v114
	v_cvt_pk_bf16_f32 v78, v78, s0
	global_store_short v[76:77], v78, off offset:1088
	v_cndmask_b32_e64 v76, v62, v46, s[60:61]
	v_add_f32_e32 v76, v102, v76
	v_mul_f32_e32 v76, 0xbfb8aa3b, v76
	v_exp_f32_e32 v76, v76
	s_nop 0
	v_add_f32_e32 v76, 1.0, v76
	v_div_scale_f32 v77, s[4:5], v76, v76, 1.0
	v_rcp_f32_e32 v78, v77
	s_nop 0
	v_fma_f32 v79, -v77, v78, 1.0
	v_fmac_f32_e32 v78, v79, v78
	v_div_scale_f32 v79, vcc, 1.0, v76, 1.0
	v_mul_f32_e32 v80, v79, v78
	v_fma_f32 v81, -v77, v80, v79
	v_fmac_f32_e32 v80, v81, v78
	v_fma_f32 v77, -v77, v80, v79
	v_div_fmas_f32 v77, v77, v78, v80
	v_div_fixup_f32 v76, v77, v76, 1.0
	v_mul_f32_e32 v76, v76, v111
	v_mul_f32_e32 v76, v76, v112
	v_cvt_pk_bf16_f32 v76, v76, s0
	global_store_short v[74:75], v76, off offset:1088
	v_cndmask_b32_e64 v74, v63, v47, s[60:61]
	v_add_f32_e32 v74, v102, v74
	v_mul_f32_e32 v74, 0xbfb8aa3b, v74
	v_exp_f32_e32 v74, v74
	s_nop 0
	v_add_f32_e32 v74, 1.0, v74
	v_div_scale_f32 v75, s[4:5], v74, v74, 1.0
	v_rcp_f32_e32 v76, v75
	s_nop 0
	v_fma_f32 v77, -v75, v76, 1.0
	v_fmac_f32_e32 v76, v77, v76
	v_div_scale_f32 v77, vcc, 1.0, v74, 1.0
	v_mul_f32_e32 v78, v77, v76
	v_fma_f32 v79, -v75, v78, v77
	v_fmac_f32_e32 v78, v79, v76
	v_fma_f32 v75, -v75, v78, v77
	v_div_fmas_f32 v75, v75, v76, v78
	v_div_fixup_f32 v74, v75, v74, 1.0
	v_mul_f32_e32 v74, v74, v109
	v_mul_f32_e32 v74, v74, v110
	v_cvt_pk_bf16_f32 v74, v74, s0
	global_store_short v[72:73], v74, off offset:1088
	v_cndmask_b32_e64 v72, v64, v48, s[60:61]
	v_add_f32_e32 v72, v102, v72
	v_mul_f32_e32 v72, 0xbfb8aa3b, v72
	v_exp_f32_e32 v72, v72
	s_nop 0
	v_add_f32_e32 v72, 1.0, v72
	v_div_scale_f32 v73, s[4:5], v72, v72, 1.0
	v_rcp_f32_e32 v74, v73
	s_nop 0
	v_fma_f32 v75, -v73, v74, 1.0
	v_fmac_f32_e32 v74, v75, v74
	v_div_scale_f32 v75, vcc, 1.0, v72, 1.0
	v_mul_f32_e32 v76, v75, v74
	v_fma_f32 v77, -v73, v76, v75
	v_fmac_f32_e32 v76, v77, v74
	v_fma_f32 v73, -v73, v76, v75
	v_div_fmas_f32 v73, v73, v74, v76
	v_div_fixup_f32 v72, v73, v72, 1.0
	v_mul_f32_e32 v72, v72, v107
	v_mul_f32_e32 v72, v72, v108
	v_cvt_pk_bf16_f32 v72, v72, s0
	global_store_short v[70:71], v72, off offset:1088
	v_cndmask_b32_e64 v70, v65, v49, s[60:61]
	v_add_f32_e32 v70, v102, v70
	v_mul_f32_e32 v70, 0xbfb8aa3b, v70
	v_exp_f32_e32 v70, v70
	s_mov_b64 s[60:61], 0
	v_add_f32_e32 v70, 1.0, v70
	v_div_scale_f32 v71, s[4:5], v70, v70, 1.0
	v_rcp_f32_e32 v72, v71
	s_mov_b32 s4, 32
	v_fma_f32 v73, -v71, v72, 1.0
	v_fmac_f32_e32 v72, v73, v72
	v_div_scale_f32 v73, vcc, 1.0, v70, 1.0
	v_mul_f32_e32 v74, v73, v72
	v_fma_f32 v75, -v71, v74, v73
	v_fmac_f32_e32 v74, v75, v72
	v_fma_f32 v71, -v71, v74, v73
	v_div_fmas_f32 v71, v71, v72, v74
	v_div_fixup_f32 v70, v71, v70, 1.0
	v_mul_f32_e32 v0, v70, v0
	v_mul_f32_e32 v0, v0, v106
	v_cvt_pk_bf16_f32 v0, v0, s0
	s_and_b64 vcc, exec, s[38:39]
	global_store_short v[68:69], v0, off offset:1088
	s_cbranch_vccz .LBB0_142

.LBB0_537:
	s_or_b64 exec, exec, s[2:3]
	s_mul_hi_i32 s2, s6, 0x2aaaaaab
	s_lshr_b32 s3, s2, 31
	s_ashr_i32 s4, s2, 3
	s_add_i32 s4, s4, s3
	s_mul_i32 s2, s4, 48
	s_sub_i32 s2, s6, s2
	v_lshl_or_b32 v8, s2, 6, v0
	v_ashrrev_i32_e32 v9, 31, v8
	v_lshlrev_b64 v[10:11], 2, v[8:9]
	v_mad_i64_i32 v[10:11], s[2:3], s4, v211, v[10:11]
	v_mov_b32_e32 v12, 0
	v_lshl_add_u64 v[10:11], v[6:7], 0, v[10:11]
	s_mov_b64 s[2:3], 0
	v_mov_b32_e32 v25, v3
	v_mov_b32_e32 v13, v12
	v_mov_b32_e32 v18, v12
	v_mov_b32_e32 v19, v12
	v_mov_b32_e32 v16, v12
	v_mov_b32_e32 v17, v12
	v_mov_b32_e32 v14, v12
	v_mov_b32_e32 v15, v12
	s_waitcnt lgkmcnt(0)
	s_barrier
	v_mov_b32_e32 v82, 0x3000
	v_mov_b32_e32 v83, 0
	v_mov_b32_e32 v84, 0x6000
	v_mov_b32_e32 v85, 0
	v_mov_b32_e32 v86, 0x9000
	v_mov_b32_e32 v87, 0
	v_mov_b32_e32 v88, 0xc000
	v_mov_b32_e32 v89, 0
	v_mov_b32_e32 v90, v10
	v_mov_b32_e32 v91, v11
	global_load_dword v66, v[90:91], off
	v_lshl_add_u64 v[92:93], v[90:91], 0, v[82:83]
	v_lshl_add_u64 v[94:95], v[90:91], 0, v[84:85]
	v_lshl_add_u64 v[96:97], v[90:91], 0, v[86:87]
	global_load_dword v67, v[92:93], off
	global_load_dword v68, v[94:95], off
	global_load_dword v69, v[96:97], off
	v_lshl_add_u64 v[90:91], v[90:91], 0, v[88:89]
	global_load_dword v70, v[90:91], off
	v_lshl_add_u64 v[92:93], v[90:91], 0, v[82:83]
	v_lshl_add_u64 v[94:95], v[90:91], 0, v[84:85]
	v_lshl_add_u64 v[96:97], v[90:91], 0, v[86:87]
	global_load_dword v71, v[92:93], off
	global_load_dword v72, v[94:95], off
	global_load_dword v73, v[96:97], off
	v_lshl_add_u64 v[90:91], v[90:91], 0, v[88:89]
	global_load_dword v74, v[90:91], off
	v_lshl_add_u64 v[92:93], v[90:91], 0, v[82:83]
	v_lshl_add_u64 v[94:95], v[90:91], 0, v[84:85]
	v_lshl_add_u64 v[96:97], v[90:91], 0, v[86:87]
	global_load_dword v75, v[92:93], off
	global_load_dword v76, v[94:95], off
	global_load_dword v77, v[96:97], off
	v_lshl_add_u64 v[90:91], v[90:91], 0, v[88:89]
	global_load_dword v78, v[90:91], off
	v_lshl_add_u64 v[92:93], v[90:91], 0, v[82:83]
	v_lshl_add_u64 v[94:95], v[90:91], 0, v[84:85]
	v_lshl_add_u64 v[96:97], v[90:91], 0, v[86:87]
	global_load_dword v79, v[92:93], off
	global_load_dword v80, v[94:95], off
	global_load_dword v81, v[96:97], off
	v_lshl_add_u64 v[90:91], v[90:91], 0, v[88:89]
	s_mov_b32 s2, 15
.Lada_loop:
	ds_read_b128 v[26:29], v25
	ds_read_b128 v[30:33], v25 offset:4096
	ds_read_b128 v[34:37], v25 offset:8192
	ds_read_b128 v[38:41], v25 offset:12288
	ds_read_b128 v[42:45], v25 offset:16384
	ds_read_b128 v[46:49], v25 offset:20480
	ds_read_b128 v[50:53], v25 offset:24576
	ds_read_b128 v[54:57], v25 offset:28672
	v_add_u32_e32 v25, 16, v25
	s_waitcnt vmcnt(12)
	s_waitcnt lgkmcnt(0)
	v_fmac_f32_e32 v18, v66, v26
	v_fmac_f32_e32 v19, v66, v30
	v_fmac_f32_e32 v16, v66, v34
	v_fmac_f32_e32 v17, v66, v38
	v_fmac_f32_e32 v14, v66, v42
	v_fmac_f32_e32 v15, v66, v46
	v_fmac_f32_e32 v12, v66, v50
	v_fmac_f32_e32 v13, v66, v54
	v_fmac_f32_e32 v18, v67, v27
	v_fmac_f32_e32 v19, v67, v31
	v_fmac_f32_e32 v16, v67, v35
	v_fmac_f32_e32 v17, v67, v39
	v_fmac_f32_e32 v14, v67, v43
	v_fmac_f32_e32 v15, v67, v47
	v_fmac_f32_e32 v12, v67, v51
	v_fmac_f32_e32 v13, v67, v55
	v_fmac_f32_e32 v18, v68, v28
	v_fmac_f32_e32 v19, v68, v32
	v_fmac_f32_e32 v16, v68, v36
	v_fmac_f32_e32 v17, v68, v40
	v_fmac_f32_e32 v14, v68, v44
	v_fmac_f32_e32 v15, v68, v48
	v_fmac_f32_e32 v12, v68, v52
	v_fmac_f32_e32 v13, v68, v56
	v_fmac_f32_e32 v18, v69, v29
	v_fmac_f32_e32 v19, v69, v33
	v_fmac_f32_e32 v16, v69, v37
	v_fmac_f32_e32 v17, v69, v41
	v_fmac_f32_e32 v14, v69, v45
	v_fmac_f32_e32 v15, v69, v49
	v_fmac_f32_e32 v12, v69, v53
	v_fmac_f32_e32 v13, v69, v57
	global_load_dword v66, v[90:91], off
	v_lshl_add_u64 v[92:93], v[90:91], 0, v[82:83]
	v_lshl_add_u64 v[94:95], v[90:91], 0, v[84:85]
	v_lshl_add_u64 v[96:97], v[90:91], 0, v[86:87]
	global_load_dword v67, v[92:93], off
	global_load_dword v68, v[94:95], off
	global_load_dword v69, v[96:97], off
	v_lshl_add_u64 v[90:91], v[90:91], 0, v[88:89]
	ds_read_b128 v[26:29], v25
	ds_read_b128 v[30:33], v25 offset:4096
	ds_read_b128 v[34:37], v25 offset:8192
	ds_read_b128 v[38:41], v25 offset:12288
	ds_read_b128 v[42:45], v25 offset:16384
	ds_read_b128 v[46:49], v25 offset:20480
	ds_read_b128 v[50:53], v25 offset:24576
	ds_read_b128 v[54:57], v25 offset:28672
	v_add_u32_e32 v25, 16, v25
	s_waitcnt vmcnt(12)
	s_waitcnt lgkmcnt(0)
	v_fmac_f32_e32 v18, v70, v26
	v_fmac_f32_e32 v19, v70, v30
	v_fmac_f32_e32 v16, v70, v34
	v_fmac_f32_e32 v17, v70, v38
	v_fmac_f32_e32 v14, v70, v42
	v_fmac_f32_e32 v15, v70, v46
	v_fmac_f32_e32 v12, v70, v50
	v_fmac_f32_e32 v13, v70, v54
	v_fmac_f32_e32 v18, v71, v27
	v_fmac_f32_e32 v19, v71, v31
	v_fmac_f32_e32 v16, v71, v35
	v_fmac_f32_e32 v17, v71, v39
	v_fmac_f32_e32 v14, v71, v43
	v_fmac_f32_e32 v15, v71, v47
	v_fmac_f32_e32 v12, v71, v51
	v_fmac_f32_e32 v13, v71, v55
	v_fmac_f32_e32 v18, v72, v28
	v_fmac_f32_e32 v19, v72, v32
	v_fmac_f32_e32 v16, v72, v36
	v_fmac_f32_e32 v17, v72, v40
	v_fmac_f32_e32 v14, v72, v44
	v_fmac_f32_e32 v15, v72, v48
	v_fmac_f32_e32 v12, v72, v52
	v_fmac_f32_e32 v13, v72, v56
	v_fmac_f32_e32 v18, v73, v29
	v_fmac_f32_e32 v19, v73, v33
	v_fmac_f32_e32 v16, v73, v37
	v_fmac_f32_e32 v17, v73, v41
	v_fmac_f32_e32 v14, v73, v45
	v_fmac_f32_e32 v15, v73, v49
	v_fmac_f32_e32 v12, v73, v53
	v_fmac_f32_e32 v13, v73, v57
	global_load_dword v70, v[90:91], off
	v_lshl_add_u64 v[92:93], v[90:91], 0, v[82:83]
	v_lshl_add_u64 v[94:95], v[90:91], 0, v[84:85]
	v_lshl_add_u64 v[96:97], v[90:91], 0, v[86:87]
	global_load_dword v71, v[92:93], off
	global_load_dword v72, v[94:95], off
	global_load_dword v73, v[96:97], off
	v_lshl_add_u64 v[90:91], v[90:91], 0, v[88:89]
	ds_read_b128 v[26:29], v25
	ds_read_b128 v[30:33], v25 offset:4096
	ds_read_b128 v[34:37], v25 offset:8192
	ds_read_b128 v[38:41], v25 offset:12288
	ds_read_b128 v[42:45], v25 offset:16384
	ds_read_b128 v[46:49], v25 offset:20480
	ds_read_b128 v[50:53], v25 offset:24576
	ds_read_b128 v[54:57], v25 offset:28672
	v_add_u32_e32 v25, 16, v25
	s_waitcnt vmcnt(12)
	s_waitcnt lgkmcnt(0)
	v_fmac_f32_e32 v18, v74, v26
	v_fmac_f32_e32 v19, v74, v30
	v_fmac_f32_e32 v16, v74, v34
	v_fmac_f32_e32 v17, v74, v38
	v_fmac_f32_e32 v14, v74, v42
	v_fmac_f32_e32 v15, v74, v46
	v_fmac_f32_e32 v12, v74, v50
	v_fmac_f32_e32 v13, v74, v54
	v_fmac_f32_e32 v18, v75, v27
	v_fmac_f32_e32 v19, v75, v31
	v_fmac_f32_e32 v16, v75, v35
	v_fmac_f32_e32 v17, v75, v39
	v_fmac_f32_e32 v14, v75, v43
	v_fmac_f32_e32 v15, v75, v47
	v_fmac_f32_e32 v12, v75, v51
	v_fmac_f32_e32 v13, v75, v55
	v_fmac_f32_e32 v18, v76, v28
	v_fmac_f32_e32 v19, v76, v32
	v_fmac_f32_e32 v16, v76, v36
	v_fmac_f32_e32 v17, v76, v40
	v_fmac_f32_e32 v14, v76, v44
	v_fmac_f32_e32 v15, v76, v48
	v_fmac_f32_e32 v12, v76, v52
	v_fmac_f32_e32 v13, v76, v56
	v_fmac_f32_e32 v18, v77, v29
	v_fmac_f32_e32 v19, v77, v33
	v_fmac_f32_e32 v16, v77, v37
	v_fmac_f32_e32 v17, v77, v41
	v_fmac_f32_e32 v14, v77, v45
	v_fmac_f32_e32 v15, v77, v49
	v_fmac_f32_e32 v12, v77, v53
	v_fmac_f32_e32 v13, v77, v57
	global_load_dword v74, v[90:91], off
	v_lshl_add_u64 v[92:93], v[90:91], 0, v[82:83]
	v_lshl_add_u64 v[94:95], v[90:91], 0, v[84:85]
	v_lshl_add_u64 v[96:97], v[90:91], 0, v[86:87]
	global_load_dword v75, v[92:93], off
	global_load_dword v76, v[94:95], off
	global_load_dword v77, v[96:97], off
	v_lshl_add_u64 v[90:91], v[90:91], 0, v[88:89]
	ds_read_b128 v[26:29], v25
	ds_read_b128 v[30:33], v25 offset:4096
	ds_read_b128 v[34:37], v25 offset:8192
	ds_read_b128 v[38:41], v25 offset:12288
	ds_read_b128 v[42:45], v25 offset:16384
	ds_read_b128 v[46:49], v25 offset:20480
	ds_read_b128 v[50:53], v25 offset:24576
	ds_read_b128 v[54:57], v25 offset:28672
	v_add_u32_e32 v25, 16, v25
	s_waitcnt vmcnt(12)
	s_waitcnt lgkmcnt(0)
	v_fmac_f32_e32 v18, v78, v26
	v_fmac_f32_e32 v19, v78, v30
	v_fmac_f32_e32 v16, v78, v34
	v_fmac_f32_e32 v17, v78, v38
	v_fmac_f32_e32 v14, v78, v42
	v_fmac_f32_e32 v15, v78, v46
	v_fmac_f32_e32 v12, v78, v50
	v_fmac_f32_e32 v13, v78, v54
	v_fmac_f32_e32 v18, v79, v27
	v_fmac_f32_e32 v19, v79, v31
	v_fmac_f32_e32 v16, v79, v35
	v_fmac_f32_e32 v17, v79, v39
	v_fmac_f32_e32 v14, v79, v43
	v_fmac_f32_e32 v15, v79, v47
	v_fmac_f32_e32 v12, v79, v51
	v_fmac_f32_e32 v13, v79, v55
	v_fmac_f32_e32 v18, v80, v28
	v_fmac_f32_e32 v19, v80, v32
	v_fmac_f32_e32 v16, v80, v36
	v_fmac_f32_e32 v17, v80, v40
	v_fmac_f32_e32 v14, v80, v44
	v_fmac_f32_e32 v15, v80, v48
	v_fmac_f32_e32 v12, v80, v52
	v_fmac_f32_e32 v13, v80, v56
	v_fmac_f32_e32 v18, v81, v29
	v_fmac_f32_e32 v19, v81, v33
	v_fmac_f32_e32 v16, v81, v37
	v_fmac_f32_e32 v17, v81, v41
	v_fmac_f32_e32 v14, v81, v45
	v_fmac_f32_e32 v15, v81, v49
	v_fmac_f32_e32 v12, v81, v53
	v_fmac_f32_e32 v13, v81, v57
	global_load_dword v78, v[90:91], off
	v_lshl_add_u64 v[92:93], v[90:91], 0, v[82:83]
	v_lshl_add_u64 v[94:95], v[90:91], 0, v[84:85]
	v_lshl_add_u64 v[96:97], v[90:91], 0, v[86:87]
	global_load_dword v79, v[92:93], off
	global_load_dword v80, v[94:95], off
	global_load_dword v81, v[96:97], off
	v_lshl_add_u64 v[90:91], v[90:91], 0, v[88:89]
	s_sub_u32 s2, s2, 1
	s_cmp_lg_u32 s2, 0
	s_cbranch_scc1 .Lada_loop
	ds_read_b128 v[26:29], v25
	ds_read_b128 v[30:33], v25 offset:4096
	ds_read_b128 v[34:37], v25 offset:8192
	ds_read_b128 v[38:41], v25 offset:12288
	ds_read_b128 v[42:45], v25 offset:16384
	ds_read_b128 v[46:49], v25 offset:20480
	ds_read_b128 v[50:53], v25 offset:24576
	ds_read_b128 v[54:57], v25 offset:28672
	v_add_u32_e32 v25, 16, v25
	s_waitcnt vmcnt(12)
	s_waitcnt lgkmcnt(0)
	v_fmac_f32_e32 v18, v66, v26
	v_fmac_f32_e32 v19, v66, v30
	v_fmac_f32_e32 v16, v66, v34
	v_fmac_f32_e32 v17, v66, v38
	v_fmac_f32_e32 v14, v66, v42
	v_fmac_f32_e32 v15, v66, v46
	v_fmac_f32_e32 v12, v66, v50
	v_fmac_f32_e32 v13, v66, v54
	v_fmac_f32_e32 v18, v67, v27
	v_fmac_f32_e32 v19, v67, v31
	v_fmac_f32_e32 v16, v67, v35
	v_fmac_f32_e32 v17, v67, v39
	v_fmac_f32_e32 v14, v67, v43
	v_fmac_f32_e32 v15, v67, v47
	v_fmac_f32_e32 v12, v67, v51
	v_fmac_f32_e32 v13, v67, v55
	v_fmac_f32_e32 v18, v68, v28
	v_fmac_f32_e32 v19, v68, v32
	v_fmac_f32_e32 v16, v68, v36
	v_fmac_f32_e32 v17, v68, v40
	v_fmac_f32_e32 v14, v68, v44
	v_fmac_f32_e32 v15, v68, v48
	v_fmac_f32_e32 v12, v68, v52
	v_fmac_f32_e32 v13, v68, v56
	v_fmac_f32_e32 v18, v69, v29
	v_fmac_f32_e32 v19, v69, v33
	v_fmac_f32_e32 v16, v69, v37
	v_fmac_f32_e32 v17, v69, v41
	v_fmac_f32_e32 v14, v69, v45
	v_fmac_f32_e32 v15, v69, v49
	v_fmac_f32_e32 v12, v69, v53
	v_fmac_f32_e32 v13, v69, v57
	ds_read_b128 v[26:29], v25
	ds_read_b128 v[30:33], v25 offset:4096
	ds_read_b128 v[34:37], v25 offset:8192
	ds_read_b128 v[38:41], v25 offset:12288
	ds_read_b128 v[42:45], v25 offset:16384
	ds_read_b128 v[46:49], v25 offset:20480
	ds_read_b128 v[50:53], v25 offset:24576
	ds_read_b128 v[54:57], v25 offset:28672
	v_add_u32_e32 v25, 16, v25
	s_waitcnt vmcnt(8)
	s_waitcnt lgkmcnt(0)
	v_fmac_f32_e32 v18, v70, v26
	v_fmac_f32_e32 v19, v70, v30
	v_fmac_f32_e32 v16, v70, v34
	v_fmac_f32_e32 v17, v70, v38
	v_fmac_f32_e32 v14, v70, v42
	v_fmac_f32_e32 v15, v70, v46
	v_fmac_f32_e32 v12, v70, v50
	v_fmac_f32_e32 v13, v70, v54
	v_fmac_f32_e32 v18, v71, v27
	v_fmac_f32_e32 v19, v71, v31
	v_fmac_f32_e32 v16, v71, v35
	v_fmac_f32_e32 v17, v71, v39
	v_fmac_f32_e32 v14, v71, v43
	v_fmac_f32_e32 v15, v71, v47
	v_fmac_f32_e32 v12, v71, v51
	v_fmac_f32_e32 v13, v71, v55
	v_fmac_f32_e32 v18, v72, v28
	v_fmac_f32_e32 v19, v72, v32
	v_fmac_f32_e32 v16, v72, v36
	v_fmac_f32_e32 v17, v72, v40
	v_fmac_f32_e32 v14, v72, v44
	v_fmac_f32_e32 v15, v72, v48
	v_fmac_f32_e32 v12, v72, v52
	v_fmac_f32_e32 v13, v72, v56
	v_fmac_f32_e32 v18, v73, v29
	v_fmac_f32_e32 v19, v73, v33
	v_fmac_f32_e32 v16, v73, v37
	v_fmac_f32_e32 v17, v73, v41
	v_fmac_f32_e32 v14, v73, v45
	v_fmac_f32_e32 v15, v73, v49
	v_fmac_f32_e32 v12, v73, v53
	v_fmac_f32_e32 v13, v73, v57
	ds_read_b128 v[26:29], v25
	ds_read_b128 v[30:33], v25 offset:4096
	ds_read_b128 v[34:37], v25 offset:8192
	ds_read_b128 v[38:41], v25 offset:12288
	ds_read_b128 v[42:45], v25 offset:16384
	ds_read_b128 v[46:49], v25 offset:20480
	ds_read_b128 v[50:53], v25 offset:24576
	ds_read_b128 v[54:57], v25 offset:28672
	v_add_u32_e32 v25, 16, v25
	s_waitcnt vmcnt(4)
	s_waitcnt lgkmcnt(0)
	v_fmac_f32_e32 v18, v74, v26
	v_fmac_f32_e32 v19, v74, v30
	v_fmac_f32_e32 v16, v74, v34
	v_fmac_f32_e32 v17, v74, v38
	v_fmac_f32_e32 v14, v74, v42
	v_fmac_f32_e32 v15, v74, v46
	v_fmac_f32_e32 v12, v74, v50
	v_fmac_f32_e32 v13, v74, v54
	v_fmac_f32_e32 v18, v75, v27
	v_fmac_f32_e32 v19, v75, v31
	v_fmac_f32_e32 v16, v75, v35
	v_fmac_f32_e32 v17, v75, v39
	v_fmac_f32_e32 v14, v75, v43
	v_fmac_f32_e32 v15, v75, v47
	v_fmac_f32_e32 v12, v75, v51
	v_fmac_f32_e32 v13, v75, v55
	v_fmac_f32_e32 v18, v76, v28
	v_fmac_f32_e32 v19, v76, v32
	v_fmac_f32_e32 v16, v76, v36
	v_fmac_f32_e32 v17, v76, v40
	v_fmac_f32_e32 v14, v76, v44
	v_fmac_f32_e32 v15, v76, v48
	v_fmac_f32_e32 v12, v76, v52
	v_fmac_f32_e32 v13, v76, v56
	v_fmac_f32_e32 v18, v77, v29
	v_fmac_f32_e32 v19, v77, v33
	v_fmac_f32_e32 v16, v77, v37
	v_fmac_f32_e32 v17, v77, v41
	v_fmac_f32_e32 v14, v77, v45
	v_fmac_f32_e32 v15, v77, v49
	v_fmac_f32_e32 v12, v77, v53
	v_fmac_f32_e32 v13, v77, v57
	ds_read_b128 v[26:29], v25
	ds_read_b128 v[30:33], v25 offset:4096
	ds_read_b128 v[34:37], v25 offset:8192
	ds_read_b128 v[38:41], v25 offset:12288
	ds_read_b128 v[42:45], v25 offset:16384
	ds_read_b128 v[46:49], v25 offset:20480
	ds_read_b128 v[50:53], v25 offset:24576
	ds_read_b128 v[54:57], v25 offset:28672
	v_add_u32_e32 v25, 16, v25
	s_waitcnt vmcnt(0)
	s_waitcnt lgkmcnt(0)
	v_fmac_f32_e32 v18, v78, v26
	v_fmac_f32_e32 v19, v78, v30
	v_fmac_f32_e32 v16, v78, v34
	v_fmac_f32_e32 v17, v78, v38
	v_fmac_f32_e32 v14, v78, v42
	v_fmac_f32_e32 v15, v78, v46
	v_fmac_f32_e32 v12, v78, v50
	v_fmac_f32_e32 v13, v78, v54
	v_fmac_f32_e32 v18, v79, v27
	v_fmac_f32_e32 v19, v79, v31
	v_fmac_f32_e32 v16, v79, v35
	v_fmac_f32_e32 v17, v79, v39
	v_fmac_f32_e32 v14, v79, v43
	v_fmac_f32_e32 v15, v79, v47
	v_fmac_f32_e32 v12, v79, v51
	v_fmac_f32_e32 v13, v79, v55
	v_fmac_f32_e32 v18, v80, v28
	v_fmac_f32_e32 v19, v80, v32
	v_fmac_f32_e32 v16, v80, v36
	v_fmac_f32_e32 v17, v80, v40
	v_fmac_f32_e32 v14, v80, v44
	v_fmac_f32_e32 v15, v80, v48
	v_fmac_f32_e32 v12, v80, v52
	v_fmac_f32_e32 v13, v80, v56
	v_fmac_f32_e32 v18, v81, v29
	v_fmac_f32_e32 v19, v81, v33
	v_fmac_f32_e32 v16, v81, v37
	v_fmac_f32_e32 v17, v81, v41
	v_fmac_f32_e32 v14, v81, v45
	v_fmac_f32_e32 v15, v81, v49
	v_fmac_f32_e32 v12, v81, v53
	v_fmac_f32_e32 v13, v81, v57
	ds_write2st64_b32 v21, v18, v19 offset0:128 offset1:129
	ds_write2st64_b32 v21, v16, v17 offset0:130 offset1:131
	ds_write2st64_b32 v21, v14, v15 offset0:132 offset1:133
	ds_write2st64_b32 v21, v12, v13 offset0:134 offset1:135
	s_waitcnt lgkmcnt(0)
	s_barrier
	s_and_saveexec_b64 s[2:3], s[40:41]
	s_cbranch_execz .LBB0_533
	s_mul_i32 s5, s4, 0xc00
	v_readlane_b32 s44, v252, 15
	s_lshl_b32 s7, s4, 3
	v_add_u32_e32 v10, s5, v8
	v_readlane_b32 s56, v252, 27
	v_readlane_b32 s57, v252, 28
	v_readlane_b32 s4, v255, 10
	v_ashrrev_i32_e32 v11, 31, v10
	v_readlane_b32 s52, v252, 23
	v_readlane_b32 s53, v252, 24
	v_readlane_b32 s56, v254, 57
	v_readlane_b32 s5, v255, 11
	v_readlane_b32 s57, v254, 58
	v_lshl_add_u64 v[10:11], v[10:11], 2, s[52:53]
	v_lshl_add_u64 v[8:9], v[8:9], 2, s[4:5]
	s_mov_b64 s[4:5], 0
	v_mov_b32_e32 v12, v24
	v_mov_b32_e32 v13, v2
	v_readlane_b32 s45, v252, 16
	v_readlane_b32 s46, v252, 17
	v_readlane_b32 s47, v252, 18
	v_readlane_b32 s48, v252, 19
	v_readlane_b32 s49, v252, 20
	v_readlane_b32 s50, v252, 21
	v_readlane_b32 s51, v252, 22
	v_readlane_b32 s54, v252, 25
	v_readlane_b32 s55, v252, 26
	v_readlane_b32 s58, v252, 29
	v_readlane_b32 s59, v252, 30
